# GEMM mainloops: removed the back-to-back s_setprio 0 / s_setprio 1 pair between the two 16-MFMA halves of each block (16 pairs)
# speedup vs baseline: 1.0019x; 1.0019x over previous
; #define PG8_STAGE(bufoff, gbase, voff) do { _Pragma("unroll") for (int _i = 0; _i < 2; ++_i) \
;         __builtin_amdgcn_global_load_lds((const unsigned*)((const char*)(gbase) + (voff)[_i]), (LAS unsigned*)(lds + (bufoff) + ldsw + _i * 8192), 16, 0, 0); } while (0)
; #define PG8_LDA(dst, b, h) do { _Pragma("unroll") for (int m = 0; m < 4; ++m) _Pragma("unroll") for (int k = 0; k < 2; ++k) dst[m][k] = *(const LAS bf16x8*)(lds + PG8_SA(b, h) + aoff + m * 2048 + k * 1024); } while (0)
; #define PG8_LDB(dst, b, h) do { _Pragma("unroll") for (int n = 0; n < 2; ++n) _Pragma("unroll") for (int k = 0; k < 2; ++k) dst[n][k] = *(const LAS bf16x8*)(lds + PG8_SB(b, h) + boff + n * 2048 + k * 1024); } while (0)
; #define PG8_MMA(ai, bj, At, Bt) do { __builtin_amdgcn_s_setprio(1); _Pragma("unroll") for (int m = 0; m < 4; ++m) _Pragma("unroll") for (int n = 0; n < 2; ++n) _Pragma("unroll") for (int k = 0; k < 2; ++k) \
;         acc[ai][bj][m][n] = __builtin_amdgcn_mfma_f32_16x16x32_bf16(Bt[n][k], At[m][k], acc[ai][bj][m][n], 0, 0, 0); __builtin_amdgcn_s_setprio(0); } while (0)
; #define PG8_WAIT_V(n) asm volatile("s_waitcnt vmcnt(" #n ")" ::: "memory")
; #define PG8_WAIT_L(n) asm volatile("s_waitcnt lgkmcnt(" #n ")" ::: "memory")
; #define PG8_BAR __builtin_amdgcn_s_barrier()
; template <class Epi, class Sched>
; __device__ __forceinline__ void gemm_phase(LAS unsigned char* lds, const Gemm g, const Sched& S, const Epi& E, const int wv) {
;     ...
;         for (int t = 0; t < nt; t += 2) {
;             const bool last = (t == nt - 2);
;             const char* a1 = cA + (size_t)(t + 1) * kstep;
;             const char* a2 = last ? nA : cA + (size_t)(t + 2) * kstep; const char* b2 = last ? nB : cB + (size_t)(t + 2) * kstep;
;             const char* a3 = a2 + kstep; const char* b3 = b2 + kstep;
;             if (last && has_next) S.a_ready(nxt);
;             PG8_LDB(B0, 0, 0); PG8_LDB(B1, 0, 1); PG8_SCHED; PG8_LDA(At, 0, 0); PG8_STAGE(PG8_SA(1, 1), a1 + hstep, voffA);
;             PG8_WAIT_V(8); PG8_WAIT_L(0); PG8_BAR; PG8_MMA(0, 0, At, B0); PG8_MMA(0, 1, At, B1); PG8_BAR; PG8_SCHED;
;             PG8_LDA(At, 0, 1); PG8_STAGE(PG8_SB(0, 0), b2, voffB); PG8_STAGE(PG8_SB(0, 1), b2 + hstep, voffB); PG8_STAGE(PG8_SA(0, 0), a2, voffA);
;             PG8_WAIT_V(8); PG8_WAIT_L(0); PG8_BAR; PG8_MMA(1, 0, At, B0); PG8_MMA(1, 1, At, B1); PG8_BAR; PG8_SCHED;
.LBB0_27:
	s_add_u32 s10, s16, 0xfff80080
	s_addc_u32 s11, s17, -1
	s_add_i32 s65, 0, 0x10000
	s_cmp_eq_u32 s52, 28
	s_cselect_b32 s13, s23, s11
	s_cselect_b32 s12, s42, s10
	v_add_u32_e32 v138, s65, v141
	s_cselect_b32 s11, s21, s45
	s_cselect_b32 s10, s43, s44
	s_add_i32 s77, 0, 0x14000
	ds_read_b128 v[144:147], v138
	ds_read_b128 v[148:151], v138 offset:1024
	ds_read_b128 v[152:155], v138 offset:2048
	ds_read_b128 v[156:159], v138 offset:3072
	v_add_u32_e32 v138, s77, v141
	ds_read_b128 v[160:163], v138
	ds_read_b128 v[164:167], v138 offset:1024
	ds_read_b128 v[168:171], v138 offset:2048
	ds_read_b128 v[172:175], v138 offset:3072
	v_lshl_add_u64 v[138:139], s[16:17], 0, v[134:135]
	s_add_i32 m0, s31, 0xc000
	ds_read_b128 v[176:179], v143
	ds_read_b128 v[180:183], v143 offset:1024
	ds_read_b128 v[184:187], v143 offset:2048
	ds_read_b128 v[188:191], v143 offset:3072
	ds_read_b128 v[192:195], v143 offset:4096
	ds_read_b128 v[196:199], v143 offset:5120
	ds_read_b128 v[200:203], v143 offset:6144
	ds_read_b128 v[204:207], v143 offset:7168
	global_load_lds_dwordx4 v[138:139], off
	v_lshl_add_u64 v[138:139], s[16:17], 0, v[136:137]
	s_add_i32 m0, s31, 0xe000
	s_nop 0
	global_load_lds_dwordx4 v[138:139], off
	s_waitcnt vmcnt(8)
	s_waitcnt lgkmcnt(0)
	s_barrier
	s_setprio 1
	s_waitcnt lgkmcnt(0)
	v_mfma_f32_16x16x32_bf16 v[124:127], v[144:147], v[176:179], v[124:127]
	v_mfma_f32_16x16x32_bf16 v[116:119], v[152:155], v[176:179], v[116:119]
	v_mfma_f32_16x16x32_bf16 v[108:111], v[144:147], v[184:187], v[108:111]
	v_mfma_f32_16x16x32_bf16 v[100:103], v[152:155], v[184:187], v[100:103]
	v_mfma_f32_16x16x32_bf16 v[92:95], v[144:147], v[192:195], v[92:95]
	v_mfma_f32_16x16x32_bf16 v[84:87], v[152:155], v[192:195], v[84:87]
	v_mfma_f32_16x16x32_bf16 v[76:79], v[144:147], v[200:203], v[76:79]
	v_mfma_f32_16x16x32_bf16 v[68:71], v[152:155], v[200:203], v[68:71]
	v_mfma_f32_16x16x32_bf16 v[124:127], v[148:151], v[180:183], v[124:127]
	v_mfma_f32_16x16x32_bf16 v[116:119], v[156:159], v[180:183], v[116:119]
	v_mfma_f32_16x16x32_bf16 v[108:111], v[148:151], v[188:191], v[108:111]
	v_mfma_f32_16x16x32_bf16 v[100:103], v[156:159], v[188:191], v[100:103]
	v_mfma_f32_16x16x32_bf16 v[92:95], v[148:151], v[196:199], v[92:95]
	v_mfma_f32_16x16x32_bf16 v[84:87], v[156:159], v[196:199], v[84:87]
	v_mfma_f32_16x16x32_bf16 v[76:79], v[148:151], v[204:207], v[76:79]
	v_mfma_f32_16x16x32_bf16 v[68:71], v[156:159], v[204:207], v[68:71]
	v_mfma_f32_16x16x32_bf16 v[120:123], v[160:163], v[176:179], v[120:123]
	v_mfma_f32_16x16x32_bf16 v[112:115], v[168:171], v[176:179], v[112:115]
	v_mfma_f32_16x16x32_bf16 v[104:107], v[160:163], v[184:187], v[104:107]
	v_mfma_f32_16x16x32_bf16 v[96:99], v[168:171], v[184:187], v[96:99]
	v_mfma_f32_16x16x32_bf16 v[88:91], v[160:163], v[192:195], v[88:91]
	v_mfma_f32_16x16x32_bf16 v[80:83], v[168:171], v[192:195], v[80:83]
	v_mfma_f32_16x16x32_bf16 v[72:75], v[160:163], v[200:203], v[72:75]
	v_mfma_f32_16x16x32_bf16 v[64:67], v[168:171], v[200:203], v[64:67]
	v_mfma_f32_16x16x32_bf16 v[120:123], v[164:167], v[180:183], v[120:123]
	v_mfma_f32_16x16x32_bf16 v[112:115], v[172:175], v[180:183], v[112:115]
	v_mfma_f32_16x16x32_bf16 v[104:107], v[164:167], v[188:191], v[104:107]
	v_mfma_f32_16x16x32_bf16 v[96:99], v[172:175], v[188:191], v[96:99]
	v_mfma_f32_16x16x32_bf16 v[88:91], v[164:167], v[196:199], v[88:91]
	v_mfma_f32_16x16x32_bf16 v[80:83], v[172:175], v[196:199], v[80:83]
	v_mfma_f32_16x16x32_bf16 v[72:75], v[164:167], v[204:207], v[72:75]
	v_mfma_f32_16x16x32_bf16 v[64:67], v[172:175], v[204:207], v[64:67]
	s_setprio 0
	s_barrier
	s_add_i32 s65, s65, s30
	v_lshl_add_u64 v[138:139], s[10:11], 0, v[210:211]
	s_mov_b32 m0, s65
	ds_read_b128 v[176:179], v143 offset:16384
	ds_read_b128 v[180:183], v143 offset:17408
	ds_read_b128 v[184:187], v143 offset:18432
	ds_read_b128 v[188:191], v143 offset:19456
	ds_read_b128 v[192:195], v143 offset:20480
	ds_read_b128 v[196:199], v143 offset:21504
	ds_read_b128 v[200:203], v143 offset:22528
	ds_read_b128 v[204:207], v143 offset:23552
	global_load_lds_dwordx4 v[138:139], off
	s_add_i32 m0, s65, 0x2000
	s_add_u32 s82, s10, 0x80000
	v_lshl_add_u64 v[208:209], s[10:11], 0, v[128:129]
	s_addc_u32 s83, s11, 0
	s_add_i32 s65, s77, s30
	global_load_lds_dwordx4 v[208:209], off
	v_lshl_add_u64 v[212:213], s[82:83], 0, v[210:211]
	s_mov_b32 m0, s65
	v_lshl_add_u64 v[214:215], s[12:13], 0, v[130:131]
	global_load_lds_dwordx4 v[212:213], off
	v_lshl_add_u64 v[212:213], s[82:83], 0, v[128:129]
	s_add_i32 m0, s65, 0x2000
	s_nop 0
	global_load_lds_dwordx4 v[212:213], off
	v_lshl_add_u64 v[212:213], s[12:13], 0, v[132:133]
	s_mov_b32 m0, s31
	s_nop 0
	global_load_lds_dwordx4 v[212:213], off
	s_mov_b32 m0, s34
	s_nop 0
	global_load_lds_dwordx4 v[214:215], off
	s_waitcnt vmcnt(8)
	s_waitcnt lgkmcnt(0)
	s_barrier
; #define PG8_STAGE(bufoff, gbase, voff) do { _Pragma("unroll") for (int _i = 0; _i < 2; ++_i) \
;         __builtin_amdgcn_global_load_lds((const unsigned*)((const char*)(gbase) + (voff)[_i]), (LAS unsigned*)(lds + (bufoff) + ldsw + _i * 8192), 16, 0, 0); } while (0)
; #define PG8_LDA(dst, b, h) do { _Pragma("unroll") for (int m = 0; m < 4; ++m) _Pragma("unroll") for (int k = 0; k < 2; ++k) dst[m][k] = *(const LAS bf16x8*)(lds + PG8_SA(b, h) + aoff + m * 2048 + k * 1024); } while (0)
; #define PG8_LDB(dst, b, h) do { _Pragma("unroll") for (int n = 0; n < 2; ++n) _Pragma("unroll") for (int k = 0; k < 2; ++k) dst[n][k] = *(const LAS bf16x8*)(lds + PG8_SB(b, h) + boff + n * 2048 + k * 1024); } while (0)
; #define PG8_MMA(ai, bj, At, Bt) do { __builtin_amdgcn_s_setprio(1); _Pragma("unroll") for (int m = 0; m < 4; ++m) _Pragma("unroll") for (int n = 0; n < 2; ++n) _Pragma("unroll") for (int k = 0; k < 2; ++k) \
;         acc[ai][bj][m][n] = __builtin_amdgcn_mfma_f32_16x16x32_bf16(Bt[n][k], At[m][k], acc[ai][bj][m][n], 0, 0, 0); __builtin_amdgcn_s_setprio(0); } while (0)
; #define PG8_WAIT_V(n) asm volatile("s_waitcnt vmcnt(" #n ")" ::: "memory")
; #define PG8_WAIT_L(n) asm volatile("s_waitcnt lgkmcnt(" #n ")" ::: "memory")
; #define PG8_BAR __builtin_amdgcn_s_barrier()
; #define PG8_SCHED __builtin_amdgcn_sched_barrier(0)
; template <class Epi, class Sched>
; __device__ __forceinline__ void gemm_phase(LAS unsigned char* lds, const Gemm g, const Sched& S, const Epi& E, const int wv) {
;     ...
;             PG8_WAIT_V(8); PG8_WAIT_L(0); PG8_BAR; PG8_MMA(1, 0, At, B0); PG8_MMA(1, 1, At, B1); PG8_BAR; PG8_SCHED;
;             PG8_LDB(B0, 1, 0); PG8_LDB(B1, 1, 1); PG8_SCHED; PG8_LDA(At, 1, 0); PG8_STAGE(PG8_SA(0, 1), a2 + hstep, voffA);
;             PG8_WAIT_V(8); PG8_WAIT_L(0); PG8_BAR; PG8_MMA(0, 0, At, B0); PG8_MMA(0, 1, At, B1); PG8_BAR; PG8_SCHED;
	s_setprio 1
	s_waitcnt lgkmcnt(0)
	v_mfma_f32_16x16x32_bf16 v[60:63], v[144:147], v[176:179], v[60:63]
	v_mfma_f32_16x16x32_bf16 v[52:55], v[152:155], v[176:179], v[52:55]
	v_mfma_f32_16x16x32_bf16 v[44:47], v[144:147], v[184:187], v[44:47]
	v_mfma_f32_16x16x32_bf16 v[36:39], v[152:155], v[184:187], v[36:39]
	v_mfma_f32_16x16x32_bf16 v[28:31], v[144:147], v[192:195], v[28:31]
	v_mfma_f32_16x16x32_bf16 v[20:23], v[152:155], v[192:195], v[20:23]
	v_mfma_f32_16x16x32_bf16 v[12:15], v[144:147], v[200:203], v[12:15]
	v_mfma_f32_16x16x32_bf16 v[4:7], v[152:155], v[200:203], v[4:7]
	v_mfma_f32_16x16x32_bf16 v[60:63], v[148:151], v[180:183], v[60:63]
	v_mfma_f32_16x16x32_bf16 v[52:55], v[156:159], v[180:183], v[52:55]
	v_mfma_f32_16x16x32_bf16 v[44:47], v[148:151], v[188:191], v[44:47]
	v_mfma_f32_16x16x32_bf16 v[36:39], v[156:159], v[188:191], v[36:39]
	v_mfma_f32_16x16x32_bf16 v[28:31], v[148:151], v[196:199], v[28:31]
	v_mfma_f32_16x16x32_bf16 v[20:23], v[156:159], v[196:199], v[20:23]
	v_mfma_f32_16x16x32_bf16 v[12:15], v[148:151], v[204:207], v[12:15]
	v_mfma_f32_16x16x32_bf16 v[4:7], v[156:159], v[204:207], v[4:7]
	v_mfma_f32_16x16x32_bf16 v[56:59], v[160:163], v[176:179], v[56:59]
	v_mfma_f32_16x16x32_bf16 v[48:51], v[168:171], v[176:179], v[48:51]
	v_mfma_f32_16x16x32_bf16 v[40:43], v[160:163], v[184:187], v[40:43]
	v_mfma_f32_16x16x32_bf16 v[32:35], v[168:171], v[184:187], v[32:35]
	v_mfma_f32_16x16x32_bf16 v[24:27], v[160:163], v[192:195], v[24:27]
	v_mfma_f32_16x16x32_bf16 v[16:19], v[168:171], v[192:195], v[16:19]
	v_mfma_f32_16x16x32_bf16 v[8:11], v[160:163], v[200:203], v[8:11]
	v_mfma_f32_16x16x32_bf16 v[0:3], v[168:171], v[200:203], v[0:3]
	v_mfma_f32_16x16x32_bf16 v[56:59], v[164:167], v[180:183], v[56:59]
	v_mfma_f32_16x16x32_bf16 v[48:51], v[172:175], v[180:183], v[48:51]
	v_mfma_f32_16x16x32_bf16 v[40:43], v[164:167], v[188:191], v[40:43]
	v_mfma_f32_16x16x32_bf16 v[32:35], v[172:175], v[188:191], v[32:35]
	v_mfma_f32_16x16x32_bf16 v[24:27], v[164:167], v[196:199], v[24:27]
	v_mfma_f32_16x16x32_bf16 v[16:19], v[172:175], v[196:199], v[16:19]
	v_mfma_f32_16x16x32_bf16 v[8:11], v[164:167], v[204:207], v[8:11]
	v_mfma_f32_16x16x32_bf16 v[0:3], v[172:175], v[204:207], v[0:3]
	s_setprio 0
	s_barrier
	s_add_i32 s65, 0, 0x18000
	s_add_i32 s77, 0, 0x1c000
	v_add_u32_e32 v156, s65, v141
	v_add_u32_e32 v172, s77, v141
	ds_read_b128 v[144:147], v156
	ds_read_b128 v[148:151], v156 offset:1024
	ds_read_b128 v[152:155], v156 offset:2048
	ds_read_b128 v[156:159], v156 offset:3072
	ds_read_b128 v[160:163], v172
	ds_read_b128 v[164:167], v172 offset:1024
	ds_read_b128 v[168:171], v172 offset:2048
	ds_read_b128 v[172:175], v172 offset:3072
	s_add_u32 s12, s12, 0x80000
	s_addc_u32 s13, s13, 0
	s_mov_b32 m0, s35
	v_lshl_add_u64 v[216:217], s[12:13], 0, v[132:133]
	ds_read_b128 v[176:179], v143 offset:32768
	ds_read_b128 v[180:183], v143 offset:33792
	ds_read_b128 v[184:187], v143 offset:34816
	ds_read_b128 v[188:191], v143 offset:35840
	ds_read_b128 v[192:195], v143 offset:36864
	ds_read_b128 v[196:199], v143 offset:37888
	ds_read_b128 v[200:203], v143 offset:38912
	ds_read_b128 v[204:207], v143 offset:39936
	global_load_lds_dwordx4 v[216:217], off
	v_lshl_add_u64 v[216:217], s[12:13], 0, v[130:131]
	s_mov_b32 m0, s36
	s_nop 0
	global_load_lds_dwordx4 v[216:217], off
	s_waitcnt vmcnt(8)
	s_waitcnt lgkmcnt(0)
	s_barrier
	s_setprio 1
	s_waitcnt lgkmcnt(0)
	v_mfma_f32_16x16x32_bf16 v[124:127], v[144:147], v[176:179], v[124:127]
	v_mfma_f32_16x16x32_bf16 v[116:119], v[152:155], v[176:179], v[116:119]
	v_mfma_f32_16x16x32_bf16 v[108:111], v[144:147], v[184:187], v[108:111]
	v_mfma_f32_16x16x32_bf16 v[100:103], v[152:155], v[184:187], v[100:103]
	v_mfma_f32_16x16x32_bf16 v[92:95], v[144:147], v[192:195], v[92:95]
	v_mfma_f32_16x16x32_bf16 v[84:87], v[152:155], v[192:195], v[84:87]
	v_mfma_f32_16x16x32_bf16 v[76:79], v[144:147], v[200:203], v[76:79]
	v_mfma_f32_16x16x32_bf16 v[68:71], v[152:155], v[200:203], v[68:71]
	v_mfma_f32_16x16x32_bf16 v[124:127], v[148:151], v[180:183], v[124:127]
	v_mfma_f32_16x16x32_bf16 v[116:119], v[156:159], v[180:183], v[116:119]
	v_mfma_f32_16x16x32_bf16 v[108:111], v[148:151], v[188:191], v[108:111]
	v_mfma_f32_16x16x32_bf16 v[100:103], v[156:159], v[188:191], v[100:103]
	v_mfma_f32_16x16x32_bf16 v[92:95], v[148:151], v[196:199], v[92:95]
	v_mfma_f32_16x16x32_bf16 v[84:87], v[156:159], v[196:199], v[84:87]
	v_mfma_f32_16x16x32_bf16 v[76:79], v[148:151], v[204:207], v[76:79]
	v_mfma_f32_16x16x32_bf16 v[68:71], v[156:159], v[204:207], v[68:71]
	v_mfma_f32_16x16x32_bf16 v[120:123], v[160:163], v[176:179], v[120:123]
	v_mfma_f32_16x16x32_bf16 v[112:115], v[168:171], v[176:179], v[112:115]
	v_mfma_f32_16x16x32_bf16 v[104:107], v[160:163], v[184:187], v[104:107]
	v_mfma_f32_16x16x32_bf16 v[96:99], v[168:171], v[184:187], v[96:99]
	v_mfma_f32_16x16x32_bf16 v[88:91], v[160:163], v[192:195], v[88:91]
	v_mfma_f32_16x16x32_bf16 v[80:83], v[168:171], v[192:195], v[80:83]
	v_mfma_f32_16x16x32_bf16 v[72:75], v[160:163], v[200:203], v[72:75]
	v_mfma_f32_16x16x32_bf16 v[64:67], v[168:171], v[200:203], v[64:67]
	v_mfma_f32_16x16x32_bf16 v[120:123], v[164:167], v[180:183], v[120:123]
	v_mfma_f32_16x16x32_bf16 v[112:115], v[172:175], v[180:183], v[112:115]
	v_mfma_f32_16x16x32_bf16 v[104:107], v[164:167], v[188:191], v[104:107]
	v_mfma_f32_16x16x32_bf16 v[96:99], v[172:175], v[188:191], v[96:99]
	v_mfma_f32_16x16x32_bf16 v[88:91], v[164:167], v[196:199], v[88:91]
	v_mfma_f32_16x16x32_bf16 v[80:83], v[172:175], v[196:199], v[80:83]
	v_mfma_f32_16x16x32_bf16 v[72:75], v[164:167], v[204:207], v[72:75]
	v_mfma_f32_16x16x32_bf16 v[64:67], v[172:175], v[204:207], v[64:67]
	s_setprio 0
	s_barrier
; #define PG8_STAGE(bufoff, gbase, voff) do { _Pragma("unroll") for (int _i = 0; _i < 2; ++_i) \
;         __builtin_amdgcn_global_load_lds((const unsigned*)((const char*)(gbase) + (voff)[_i]), (LAS unsigned*)(lds + (bufoff) + ldsw + _i * 8192), 16, 0, 0); } while (0)
; #define PG8_LDA(dst, b, h) do { _Pragma("unroll") for (int m = 0; m < 4; ++m) _Pragma("unroll") for (int k = 0; k < 2; ++k) dst[m][k] = *(const LAS bf16x8*)(lds + PG8_SA(b, h) + aoff + m * 2048 + k * 1024); } while (0)
; #define PG8_MMA(ai, bj, At, Bt) do { __builtin_amdgcn_s_setprio(1); _Pragma("unroll") for (int m = 0; m < 4; ++m) _Pragma("unroll") for (int n = 0; n < 2; ++n) _Pragma("unroll") for (int k = 0; k < 2; ++k) \
;         acc[ai][bj][m][n] = __builtin_amdgcn_mfma_f32_16x16x32_bf16(Bt[n][k], At[m][k], acc[ai][bj][m][n], 0, 0, 0); __builtin_amdgcn_s_setprio(0); } while (0)
; #define PG8_WAIT_V(n) asm volatile("s_waitcnt vmcnt(" #n ")" ::: "memory")
; #define PG8_WAIT_L(n) asm volatile("s_waitcnt lgkmcnt(" #n ")" ::: "memory")
; #define PG8_BAR __builtin_amdgcn_s_barrier()
; #define PG8_SCHED __builtin_amdgcn_sched_barrier(0)
; template <class Epi, class Sched>
; __device__ __forceinline__ void gemm_phase(LAS unsigned char* lds, const Gemm g, const Sched& S, const Epi& E, const int wv) {
;     ...
;             PG8_LDA(At, 1, 1); PG8_STAGE(PG8_SB(1, 0), b3, voffB); PG8_STAGE(PG8_SB(1, 1), b3 + hstep, voffB); PG8_STAGE(PG8_SA(1, 0), a3, voffA);
;             PG8_WAIT_V(8); PG8_WAIT_L(0); PG8_BAR; PG8_MMA(1, 0, At, B0); PG8_MMA(1, 1, At, B1); PG8_BAR; PG8_SCHED;
;         }
;         if (wr == 0) PG8_BAR;
	s_add_i32 s12, s65, s30
	v_lshl_add_u64 v[138:139], v[138:139], 0, s[46:47]
	s_mov_b32 m0, s12
	ds_read_b128 v[176:179], v143 offset:49152
	ds_read_b128 v[180:183], v143 offset:50176
	ds_read_b128 v[184:187], v143 offset:51200
	ds_read_b128 v[188:191], v143 offset:52224
	ds_read_b128 v[192:195], v143 offset:53248
	ds_read_b128 v[196:199], v143 offset:54272
	ds_read_b128 v[200:203], v143 offset:55296
	ds_read_b128 v[204:207], v143 offset:56320
	global_load_lds_dwordx4 v[138:139], off
	s_add_i32 m0, s12, 0x2000
	s_add_u32 s10, s10, 0x80080
	v_lshl_add_u64 v[138:139], v[208:209], 0, s[46:47]
	s_addc_u32 s11, s11, 0
	s_add_i32 s12, s77, s30
	global_load_lds_dwordx4 v[138:139], off
	v_lshl_add_u64 v[138:139], s[10:11], 0, v[210:211]
	s_mov_b32 m0, s12
	s_nop 0
	global_load_lds_dwordx4 v[138:139], off
	v_lshl_add_u64 v[138:139], s[10:11], 0, v[128:129]
	s_add_i32 m0, s12, 0x2000
	s_nop 0
	global_load_lds_dwordx4 v[138:139], off
	v_lshl_add_u64 v[138:139], v[212:213], 0, s[46:47]
	s_mov_b32 m0, s37
	s_nop 0
	global_load_lds_dwordx4 v[138:139], off
	v_lshl_add_u64 v[138:139], v[214:215], 0, s[46:47]
	s_mov_b32 m0, s38
	s_nop 0
	global_load_lds_dwordx4 v[138:139], off
	s_waitcnt vmcnt(8)
	s_waitcnt lgkmcnt(0)
	s_barrier
	s_setprio 1
	s_waitcnt lgkmcnt(0)
	v_mfma_f32_16x16x32_bf16 v[60:63], v[144:147], v[176:179], v[60:63]
	v_mfma_f32_16x16x32_bf16 v[52:55], v[152:155], v[176:179], v[52:55]
	v_mfma_f32_16x16x32_bf16 v[44:47], v[144:147], v[184:187], v[44:47]
	v_mfma_f32_16x16x32_bf16 v[36:39], v[152:155], v[184:187], v[36:39]
	v_mfma_f32_16x16x32_bf16 v[28:31], v[144:147], v[192:195], v[28:31]
	v_mfma_f32_16x16x32_bf16 v[20:23], v[152:155], v[192:195], v[20:23]
	v_mfma_f32_16x16x32_bf16 v[12:15], v[144:147], v[200:203], v[12:15]
	v_mfma_f32_16x16x32_bf16 v[4:7], v[152:155], v[200:203], v[4:7]
	v_mfma_f32_16x16x32_bf16 v[60:63], v[148:151], v[180:183], v[60:63]
	v_mfma_f32_16x16x32_bf16 v[52:55], v[156:159], v[180:183], v[52:55]
	v_mfma_f32_16x16x32_bf16 v[44:47], v[148:151], v[188:191], v[44:47]
	v_mfma_f32_16x16x32_bf16 v[36:39], v[156:159], v[188:191], v[36:39]
	v_mfma_f32_16x16x32_bf16 v[28:31], v[148:151], v[196:199], v[28:31]
	v_mfma_f32_16x16x32_bf16 v[20:23], v[156:159], v[196:199], v[20:23]
	v_mfma_f32_16x16x32_bf16 v[12:15], v[148:151], v[204:207], v[12:15]
	v_mfma_f32_16x16x32_bf16 v[4:7], v[156:159], v[204:207], v[4:7]
	v_mfma_f32_16x16x32_bf16 v[56:59], v[160:163], v[176:179], v[56:59]
	v_mfma_f32_16x16x32_bf16 v[48:51], v[168:171], v[176:179], v[48:51]
	v_mfma_f32_16x16x32_bf16 v[40:43], v[160:163], v[184:187], v[40:43]
	v_mfma_f32_16x16x32_bf16 v[32:35], v[168:171], v[184:187], v[32:35]
	v_mfma_f32_16x16x32_bf16 v[24:27], v[160:163], v[192:195], v[24:27]
	v_mfma_f32_16x16x32_bf16 v[16:19], v[168:171], v[192:195], v[16:19]
	v_mfma_f32_16x16x32_bf16 v[8:11], v[160:163], v[200:203], v[8:11]
	v_mfma_f32_16x16x32_bf16 v[0:3], v[168:171], v[200:203], v[0:3]
	v_mfma_f32_16x16x32_bf16 v[56:59], v[164:167], v[180:183], v[56:59]
	v_mfma_f32_16x16x32_bf16 v[48:51], v[172:175], v[180:183], v[48:51]
	v_mfma_f32_16x16x32_bf16 v[40:43], v[164:167], v[188:191], v[40:43]
	v_mfma_f32_16x16x32_bf16 v[32:35], v[172:175], v[188:191], v[32:35]
	v_mfma_f32_16x16x32_bf16 v[24:27], v[164:167], v[196:199], v[24:27]
	v_mfma_f32_16x16x32_bf16 v[16:19], v[172:175], v[196:199], v[16:19]
	v_mfma_f32_16x16x32_bf16 v[8:11], v[164:167], v[204:207], v[8:11]
	v_mfma_f32_16x16x32_bf16 v[0:3], v[172:175], v[204:207], v[0:3]
	s_setprio 0
	s_barrier
	s_add_i32 s52, s52, 2
	s_add_u32 s16, s16, 0x100
	s_addc_u32 s17, s17, 0
	s_add_u32 s44, s44, 0x100
	s_addc_u32 s45, s45, 0
	s_cmp_gt_u32 s52, 29
	s_cbranch_scc0 .LBB0_27
	s_and_b64 vcc, exec, s[18:19]
	s_cbranch_vccz .LBB0_30
	s_barrier

; #define PG8_STAGE(bufoff, gbase, voff) do { _Pragma("unroll") for (int _i = 0; _i < 2; ++_i) \
;         __builtin_amdgcn_global_load_lds((const unsigned*)((const char*)(gbase) + (voff)[_i]), (LAS unsigned*)(lds + (bufoff) + ldsw + _i * 8192), 16, 0, 0); } while (0)
; #define PG8_LDA(dst, b, h) do { _Pragma("unroll") for (int m = 0; m < 4; ++m) _Pragma("unroll") for (int k = 0; k < 2; ++k) dst[m][k] = *(const LAS bf16x8*)(lds + PG8_SA(b, h) + aoff + m * 2048 + k * 1024); } while (0)
; #define PG8_LDB(dst, b, h) do { _Pragma("unroll") for (int n = 0; n < 2; ++n) _Pragma("unroll") for (int k = 0; k < 2; ++k) dst[n][k] = *(const LAS bf16x8*)(lds + PG8_SB(b, h) + boff + n * 2048 + k * 1024); } while (0)
; #define PG8_MMA(ai, bj, At, Bt) do { __builtin_amdgcn_s_setprio(1); _Pragma("unroll") for (int m = 0; m < 4; ++m) _Pragma("unroll") for (int n = 0; n < 2; ++n) _Pragma("unroll") for (int k = 0; k < 2; ++k) \
;         acc[ai][bj][m][n] = __builtin_amdgcn_mfma_f32_16x16x32_bf16(Bt[n][k], At[m][k], acc[ai][bj][m][n], 0, 0, 0); __builtin_amdgcn_s_setprio(0); } while (0)
; #define PG8_WAIT_V(n) asm volatile("s_waitcnt vmcnt(" #n ")" ::: "memory")
; #define PG8_WAIT_L(n) asm volatile("s_waitcnt lgkmcnt(" #n ")" ::: "memory")
; #define PG8_BAR __builtin_amdgcn_s_barrier()
; template <class Epi, class Sched>
; __device__ __forceinline__ void gemm_phase(LAS unsigned char* lds, const Gemm g, const Sched& S, const Epi& E, const int wv) {
;     ...
;         for (int t = 0; t < nt; t += 2) {
;             const bool last = (t == nt - 2);
;             const char* a1 = cA + (size_t)(t + 1) * kstep;
;             const char* a2 = last ? nA : cA + (size_t)(t + 2) * kstep; const char* b2 = last ? nB : cB + (size_t)(t + 2) * kstep;
;             const char* a3 = a2 + kstep; const char* b3 = b2 + kstep;
;             if (last && has_next) S.a_ready(nxt);
;             PG8_LDB(B0, 0, 0); PG8_LDB(B1, 0, 1); PG8_SCHED; PG8_LDA(At, 0, 0); PG8_STAGE(PG8_SA(1, 1), a1 + hstep, voffA);
;             PG8_WAIT_V(8); PG8_WAIT_L(0); PG8_BAR; PG8_MMA(0, 0, At, B0); PG8_MMA(0, 1, At, B1); PG8_BAR; PG8_SCHED;
;             PG8_LDA(At, 0, 1); PG8_STAGE(PG8_SB(0, 0), b2, voffB); PG8_STAGE(PG8_SB(0, 1), b2 + hstep, voffB); PG8_STAGE(PG8_SA(0, 0), a2, voffA);
;             PG8_WAIT_V(8); PG8_WAIT_L(0); PG8_BAR; PG8_MMA(1, 0, At, B0); PG8_MMA(1, 1, At, B1); PG8_BAR; PG8_SCHED;
.LBB0_81:
	s_add_i32 s44, s10, 2
	s_add_u32 s45, s24, 0x80
	s_addc_u32 s11, s25, 0
	s_add_i32 s52, 0, 0x10000
	s_cmp_eq_u32 s36, s10
	s_cselect_b32 s11, s7, s11
	s_cselect_b32 s10, s6, s45
	v_add_u32_e32 v138, s52, v142
	s_cselect_b32 s83, s23, s13
	s_cselect_b32 s82, s22, s12
	s_add_i32 s45, 0, 0x14000
	ds_read_b128 v[146:149], v138
	ds_read_b128 v[150:153], v138 offset:1024
	ds_read_b128 v[154:157], v138 offset:2048
	ds_read_b128 v[158:161], v138 offset:3072
	v_add_u32_e32 v138, s45, v142
	ds_read_b128 v[162:165], v138
	ds_read_b128 v[166:169], v138 offset:1024
	ds_read_b128 v[170:173], v138 offset:2048
	ds_read_b128 v[174:177], v138 offset:3072
	v_lshl_add_u64 v[140:141], s[24:25], 0, v[134:135]
	s_add_i32 m0, s27, 0xc000
	ds_read_b128 v[178:181], v144
	ds_read_b128 v[182:185], v144 offset:1024
	ds_read_b128 v[186:189], v144 offset:2048
	ds_read_b128 v[190:193], v144 offset:3072
	ds_read_b128 v[194:197], v144 offset:4096
	ds_read_b128 v[198:201], v144 offset:5120
	ds_read_b128 v[202:205], v144 offset:6144
	ds_read_b128 v[206:209], v144 offset:7168
	global_load_lds_dwordx4 v[140:141], off
	v_lshl_add_u64 v[140:141], s[24:25], 0, v[136:137]
	s_add_i32 m0, s27, 0xe000
	s_nop 0
	global_load_lds_dwordx4 v[140:141], off
	s_waitcnt vmcnt(8)
	s_waitcnt lgkmcnt(0)
	s_barrier
	s_setprio 1
	s_waitcnt lgkmcnt(0)
	v_mfma_f32_16x16x32_bf16 v[124:127], v[146:149], v[178:181], v[124:127]
	v_mfma_f32_16x16x32_bf16 v[120:123], v[154:157], v[178:181], v[120:123]
	v_mfma_f32_16x16x32_bf16 v[112:115], v[146:149], v[186:189], v[112:115]
	v_mfma_f32_16x16x32_bf16 v[104:107], v[154:157], v[186:189], v[104:107]
	v_mfma_f32_16x16x32_bf16 v[96:99], v[146:149], v[194:197], v[96:99]
	v_mfma_f32_16x16x32_bf16 v[88:91], v[154:157], v[194:197], v[88:91]
	v_mfma_f32_16x16x32_bf16 v[80:83], v[146:149], v[202:205], v[80:83]
	v_mfma_f32_16x16x32_bf16 v[72:75], v[154:157], v[202:205], v[72:75]
	v_mfma_f32_16x16x32_bf16 v[124:127], v[150:153], v[182:185], v[124:127]
	v_mfma_f32_16x16x32_bf16 v[120:123], v[158:161], v[182:185], v[120:123]
	v_mfma_f32_16x16x32_bf16 v[112:115], v[150:153], v[190:193], v[112:115]
	v_mfma_f32_16x16x32_bf16 v[104:107], v[158:161], v[190:193], v[104:107]
	v_mfma_f32_16x16x32_bf16 v[96:99], v[150:153], v[198:201], v[96:99]
	v_mfma_f32_16x16x32_bf16 v[88:91], v[158:161], v[198:201], v[88:91]
	v_mfma_f32_16x16x32_bf16 v[80:83], v[150:153], v[206:209], v[80:83]
	v_mfma_f32_16x16x32_bf16 v[72:75], v[158:161], v[206:209], v[72:75]
	v_mfma_f32_16x16x32_bf16 v[116:119], v[162:165], v[178:181], v[116:119]
	v_mfma_f32_16x16x32_bf16 v[108:111], v[170:173], v[178:181], v[108:111]
	v_mfma_f32_16x16x32_bf16 v[100:103], v[162:165], v[186:189], v[100:103]
	v_mfma_f32_16x16x32_bf16 v[92:95], v[170:173], v[186:189], v[92:95]
	v_mfma_f32_16x16x32_bf16 v[84:87], v[162:165], v[194:197], v[84:87]
	v_mfma_f32_16x16x32_bf16 v[76:79], v[170:173], v[194:197], v[76:79]
	v_mfma_f32_16x16x32_bf16 v[68:71], v[162:165], v[202:205], v[68:71]
	v_mfma_f32_16x16x32_bf16 v[64:67], v[170:173], v[202:205], v[64:67]
	v_mfma_f32_16x16x32_bf16 v[116:119], v[166:169], v[182:185], v[116:119]
	v_mfma_f32_16x16x32_bf16 v[108:111], v[174:177], v[182:185], v[108:111]
	v_mfma_f32_16x16x32_bf16 v[100:103], v[166:169], v[190:193], v[100:103]
	v_mfma_f32_16x16x32_bf16 v[92:95], v[174:177], v[190:193], v[92:95]
	v_mfma_f32_16x16x32_bf16 v[84:87], v[166:169], v[198:201], v[84:87]
	v_mfma_f32_16x16x32_bf16 v[76:79], v[174:177], v[198:201], v[76:79]
	v_mfma_f32_16x16x32_bf16 v[68:71], v[166:169], v[206:209], v[68:71]
	v_mfma_f32_16x16x32_bf16 v[64:67], v[174:177], v[206:209], v[64:67]
	s_setprio 0
	s_barrier
	s_add_i32 s52, s52, s26
	v_lshl_add_u64 v[140:141], s[82:83], 0, v[210:211]
	s_mov_b32 m0, s52
	ds_read_b128 v[178:181], v144 offset:16384
	ds_read_b128 v[182:185], v144 offset:17408
	ds_read_b128 v[186:189], v144 offset:18432
	ds_read_b128 v[190:193], v144 offset:19456
	ds_read_b128 v[194:197], v144 offset:20480
	ds_read_b128 v[198:201], v144 offset:21504
	ds_read_b128 v[202:205], v144 offset:22528
	ds_read_b128 v[206:209], v144 offset:23552
	global_load_lds_dwordx4 v[140:141], off
	s_add_i32 m0, s52, 0x2000
	v_lshl_add_u64 v[212:213], s[82:83], 0, v[128:129]
	s_add_u32 s82, s82, s38
	s_addc_u32 s83, s83, 0
	s_add_i32 s45, s45, s26
	global_load_lds_dwordx4 v[212:213], off
	v_lshl_add_u64 v[214:215], s[82:83], 0, v[210:211]
	s_mov_b32 m0, s45
	v_lshl_add_u64 v[216:217], s[82:83], 0, v[128:129]
	global_load_lds_dwordx4 v[214:215], off
	s_add_i32 m0, s45, 0x2000
	v_lshl_add_u64 v[218:219], s[10:11], 0, v[132:133]
	global_load_lds_dwordx4 v[216:217], off
	s_mov_b32 m0, s27
	v_lshl_add_u64 v[220:221], s[10:11], 0, v[130:131]
	global_load_lds_dwordx4 v[218:219], off
	s_mov_b32 m0, s28
	s_nop 0
	global_load_lds_dwordx4 v[220:221], off
	s_waitcnt vmcnt(8)
	s_waitcnt lgkmcnt(0)
	s_barrier
; #define PG8_STAGE(bufoff, gbase, voff) do { _Pragma("unroll") for (int _i = 0; _i < 2; ++_i) \
;         __builtin_amdgcn_global_load_lds((const unsigned*)((const char*)(gbase) + (voff)[_i]), (LAS unsigned*)(lds + (bufoff) + ldsw + _i * 8192), 16, 0, 0); } while (0)
; #define PG8_LDA(dst, b, h) do { _Pragma("unroll") for (int m = 0; m < 4; ++m) _Pragma("unroll") for (int k = 0; k < 2; ++k) dst[m][k] = *(const LAS bf16x8*)(lds + PG8_SA(b, h) + aoff + m * 2048 + k * 1024); } while (0)
; #define PG8_LDB(dst, b, h) do { _Pragma("unroll") for (int n = 0; n < 2; ++n) _Pragma("unroll") for (int k = 0; k < 2; ++k) dst[n][k] = *(const LAS bf16x8*)(lds + PG8_SB(b, h) + boff + n * 2048 + k * 1024); } while (0)
; #define PG8_MMA(ai, bj, At, Bt) do { __builtin_amdgcn_s_setprio(1); _Pragma("unroll") for (int m = 0; m < 4; ++m) _Pragma("unroll") for (int n = 0; n < 2; ++n) _Pragma("unroll") for (int k = 0; k < 2; ++k) \
;         acc[ai][bj][m][n] = __builtin_amdgcn_mfma_f32_16x16x32_bf16(Bt[n][k], At[m][k], acc[ai][bj][m][n], 0, 0, 0); __builtin_amdgcn_s_setprio(0); } while (0)
; #define PG8_WAIT_V(n) asm volatile("s_waitcnt vmcnt(" #n ")" ::: "memory")
; #define PG8_WAIT_L(n) asm volatile("s_waitcnt lgkmcnt(" #n ")" ::: "memory")
; #define PG8_BAR __builtin_amdgcn_s_barrier()
; #define PG8_SCHED __builtin_amdgcn_sched_barrier(0)
; template <class Epi, class Sched>
; __device__ __forceinline__ void gemm_phase(LAS unsigned char* lds, const Gemm g, const Sched& S, const Epi& E, const int wv) {
;     ...
;             PG8_WAIT_V(8); PG8_WAIT_L(0); PG8_BAR; PG8_MMA(1, 0, At, B0); PG8_MMA(1, 1, At, B1); PG8_BAR; PG8_SCHED;
;             PG8_LDB(B0, 1, 0); PG8_LDB(B1, 1, 1); PG8_SCHED; PG8_LDA(At, 1, 0); PG8_STAGE(PG8_SA(0, 1), a2 + hstep, voffA);
;             PG8_WAIT_V(8); PG8_WAIT_L(0); PG8_BAR; PG8_MMA(0, 0, At, B0); PG8_MMA(0, 1, At, B1); PG8_BAR; PG8_SCHED;
	s_setprio 1
	s_waitcnt lgkmcnt(0)
	v_mfma_f32_16x16x32_bf16 v[60:63], v[146:149], v[178:181], v[60:63]
	v_mfma_f32_16x16x32_bf16 v[56:59], v[154:157], v[178:181], v[56:59]
	v_mfma_f32_16x16x32_bf16 v[48:51], v[146:149], v[186:189], v[48:51]
	v_mfma_f32_16x16x32_bf16 v[40:43], v[154:157], v[186:189], v[40:43]
	v_mfma_f32_16x16x32_bf16 v[32:35], v[146:149], v[194:197], v[32:35]
	v_mfma_f32_16x16x32_bf16 v[24:27], v[154:157], v[194:197], v[24:27]
	v_mfma_f32_16x16x32_bf16 v[16:19], v[146:149], v[202:205], v[16:19]
	v_mfma_f32_16x16x32_bf16 v[8:11], v[154:157], v[202:205], v[8:11]
	v_mfma_f32_16x16x32_bf16 v[60:63], v[150:153], v[182:185], v[60:63]
	v_mfma_f32_16x16x32_bf16 v[56:59], v[158:161], v[182:185], v[56:59]
	v_mfma_f32_16x16x32_bf16 v[48:51], v[150:153], v[190:193], v[48:51]
	v_mfma_f32_16x16x32_bf16 v[40:43], v[158:161], v[190:193], v[40:43]
	v_mfma_f32_16x16x32_bf16 v[32:35], v[150:153], v[198:201], v[32:35]
	v_mfma_f32_16x16x32_bf16 v[24:27], v[158:161], v[198:201], v[24:27]
	v_mfma_f32_16x16x32_bf16 v[16:19], v[150:153], v[206:209], v[16:19]
	v_mfma_f32_16x16x32_bf16 v[8:11], v[158:161], v[206:209], v[8:11]
	v_mfma_f32_16x16x32_bf16 v[52:55], v[162:165], v[178:181], v[52:55]
	v_mfma_f32_16x16x32_bf16 v[44:47], v[170:173], v[178:181], v[44:47]
	v_mfma_f32_16x16x32_bf16 v[36:39], v[162:165], v[186:189], v[36:39]
	v_mfma_f32_16x16x32_bf16 v[28:31], v[170:173], v[186:189], v[28:31]
	v_mfma_f32_16x16x32_bf16 v[20:23], v[162:165], v[194:197], v[20:23]
	v_mfma_f32_16x16x32_bf16 v[12:15], v[170:173], v[194:197], v[12:15]
	v_mfma_f32_16x16x32_bf16 v[4:7], v[162:165], v[202:205], v[4:7]
	v_mfma_f32_16x16x32_bf16 v[0:3], v[170:173], v[202:205], v[0:3]
	v_mfma_f32_16x16x32_bf16 v[52:55], v[166:169], v[182:185], v[52:55]
	v_mfma_f32_16x16x32_bf16 v[44:47], v[174:177], v[182:185], v[44:47]
	v_mfma_f32_16x16x32_bf16 v[36:39], v[166:169], v[190:193], v[36:39]
	v_mfma_f32_16x16x32_bf16 v[28:31], v[174:177], v[190:193], v[28:31]
	v_mfma_f32_16x16x32_bf16 v[20:23], v[166:169], v[198:201], v[20:23]
	v_mfma_f32_16x16x32_bf16 v[12:15], v[174:177], v[198:201], v[12:15]
	v_mfma_f32_16x16x32_bf16 v[4:7], v[166:169], v[206:209], v[4:7]
	v_mfma_f32_16x16x32_bf16 v[0:3], v[174:177], v[206:209], v[0:3]
	s_setprio 0
	s_barrier
	s_add_i32 s45, 0, 0x18000
	v_add_u32_e32 v138, s45, v142
	s_add_i32 s52, 0, 0x1c000
	ds_read_b128 v[146:149], v138
	ds_read_b128 v[150:153], v138 offset:1024
	ds_read_b128 v[154:157], v138 offset:2048
	ds_read_b128 v[158:161], v138 offset:3072
	v_add_u32_e32 v138, s52, v142
	ds_read_b128 v[162:165], v138
	ds_read_b128 v[166:169], v138 offset:1024
	ds_read_b128 v[170:173], v138 offset:2048
	ds_read_b128 v[174:177], v138 offset:3072
	s_add_u32 s10, s10, s38
	s_addc_u32 s11, s11, 0
	s_mov_b32 m0, s29
	v_lshl_add_u64 v[222:223], s[10:11], 0, v[132:133]
	ds_read_b128 v[178:181], v144 offset:32768
	ds_read_b128 v[182:185], v144 offset:33792
	ds_read_b128 v[186:189], v144 offset:34816
	ds_read_b128 v[190:193], v144 offset:35840
	ds_read_b128 v[194:197], v144 offset:36864
	ds_read_b128 v[198:201], v144 offset:37888
	ds_read_b128 v[202:205], v144 offset:38912
	ds_read_b128 v[206:209], v144 offset:39936
	global_load_lds_dwordx4 v[222:223], off
	v_lshl_add_u64 v[222:223], s[10:11], 0, v[130:131]
	s_mov_b32 m0, s30
	s_nop 0
	global_load_lds_dwordx4 v[222:223], off
	s_waitcnt vmcnt(8)
	s_waitcnt lgkmcnt(0)
	s_barrier
	s_setprio 1
	s_waitcnt lgkmcnt(0)
	v_mfma_f32_16x16x32_bf16 v[124:127], v[146:149], v[178:181], v[124:127]
	v_mfma_f32_16x16x32_bf16 v[120:123], v[154:157], v[178:181], v[120:123]
	v_mfma_f32_16x16x32_bf16 v[112:115], v[146:149], v[186:189], v[112:115]
	v_mfma_f32_16x16x32_bf16 v[104:107], v[154:157], v[186:189], v[104:107]
	v_mfma_f32_16x16x32_bf16 v[96:99], v[146:149], v[194:197], v[96:99]
	v_mfma_f32_16x16x32_bf16 v[88:91], v[154:157], v[194:197], v[88:91]
	v_mfma_f32_16x16x32_bf16 v[80:83], v[146:149], v[202:205], v[80:83]
	v_mfma_f32_16x16x32_bf16 v[72:75], v[154:157], v[202:205], v[72:75]
	v_mfma_f32_16x16x32_bf16 v[124:127], v[150:153], v[182:185], v[124:127]
	v_mfma_f32_16x16x32_bf16 v[120:123], v[158:161], v[182:185], v[120:123]
	v_mfma_f32_16x16x32_bf16 v[112:115], v[150:153], v[190:193], v[112:115]
	v_mfma_f32_16x16x32_bf16 v[104:107], v[158:161], v[190:193], v[104:107]
	v_mfma_f32_16x16x32_bf16 v[96:99], v[150:153], v[198:201], v[96:99]
	v_mfma_f32_16x16x32_bf16 v[88:91], v[158:161], v[198:201], v[88:91]
	v_mfma_f32_16x16x32_bf16 v[80:83], v[150:153], v[206:209], v[80:83]
	v_mfma_f32_16x16x32_bf16 v[72:75], v[158:161], v[206:209], v[72:75]
	v_mfma_f32_16x16x32_bf16 v[116:119], v[162:165], v[178:181], v[116:119]
	v_mfma_f32_16x16x32_bf16 v[108:111], v[170:173], v[178:181], v[108:111]
	v_mfma_f32_16x16x32_bf16 v[100:103], v[162:165], v[186:189], v[100:103]
	v_mfma_f32_16x16x32_bf16 v[92:95], v[170:173], v[186:189], v[92:95]
	v_mfma_f32_16x16x32_bf16 v[84:87], v[162:165], v[194:197], v[84:87]
	v_mfma_f32_16x16x32_bf16 v[76:79], v[170:173], v[194:197], v[76:79]
	v_mfma_f32_16x16x32_bf16 v[68:71], v[162:165], v[202:205], v[68:71]
	v_mfma_f32_16x16x32_bf16 v[64:67], v[170:173], v[202:205], v[64:67]
	v_mfma_f32_16x16x32_bf16 v[116:119], v[166:169], v[182:185], v[116:119]
	v_mfma_f32_16x16x32_bf16 v[108:111], v[174:177], v[182:185], v[108:111]
	v_mfma_f32_16x16x32_bf16 v[100:103], v[166:169], v[190:193], v[100:103]
	v_mfma_f32_16x16x32_bf16 v[92:95], v[174:177], v[190:193], v[92:95]
	v_mfma_f32_16x16x32_bf16 v[84:87], v[166:169], v[198:201], v[84:87]
	v_mfma_f32_16x16x32_bf16 v[76:79], v[174:177], v[198:201], v[76:79]
	v_mfma_f32_16x16x32_bf16 v[68:71], v[166:169], v[206:209], v[68:71]
	v_mfma_f32_16x16x32_bf16 v[64:67], v[174:177], v[206:209], v[64:67]
	s_setprio 0
	s_barrier
; #define PG8_STAGE(bufoff, gbase, voff) do { _Pragma("unroll") for (int _i = 0; _i < 2; ++_i) \
;         __builtin_amdgcn_global_load_lds((const unsigned*)((const char*)(gbase) + (voff)[_i]), (LAS unsigned*)(lds + (bufoff) + ldsw + _i * 8192), 16, 0, 0); } while (0)
; #define PG8_LDA(dst, b, h) do { _Pragma("unroll") for (int m = 0; m < 4; ++m) _Pragma("unroll") for (int k = 0; k < 2; ++k) dst[m][k] = *(const LAS bf16x8*)(lds + PG8_SA(b, h) + aoff + m * 2048 + k * 1024); } while (0)
; #define PG8_MMA(ai, bj, At, Bt) do { __builtin_amdgcn_s_setprio(1); _Pragma("unroll") for (int m = 0; m < 4; ++m) _Pragma("unroll") for (int n = 0; n < 2; ++n) _Pragma("unroll") for (int k = 0; k < 2; ++k) \
;         acc[ai][bj][m][n] = __builtin_amdgcn_mfma_f32_16x16x32_bf16(Bt[n][k], At[m][k], acc[ai][bj][m][n], 0, 0, 0); __builtin_amdgcn_s_setprio(0); } while (0)
; #define PG8_WAIT_V(n) asm volatile("s_waitcnt vmcnt(" #n ")" ::: "memory")
; #define PG8_WAIT_L(n) asm volatile("s_waitcnt lgkmcnt(" #n ")" ::: "memory")
; #define PG8_BAR __builtin_amdgcn_s_barrier()
; #define PG8_SCHED __builtin_amdgcn_sched_barrier(0)
; template <class Epi, class Sched>
; __device__ __forceinline__ void gemm_phase(LAS unsigned char* lds, const Gemm g, const Sched& S, const Epi& E, const int wv) {
;     ...
;             PG8_LDA(At, 1, 1); PG8_STAGE(PG8_SB(1, 0), b3, voffB); PG8_STAGE(PG8_SB(1, 1), b3 + hstep, voffB); PG8_STAGE(PG8_SA(1, 0), a3, voffA);
;             PG8_WAIT_V(8); PG8_WAIT_L(0); PG8_BAR; PG8_MMA(1, 0, At, B0); PG8_MMA(1, 1, At, B1); PG8_BAR; PG8_SCHED;
;         }
;         if (wr == 0) PG8_BAR;
	s_add_i32 s10, s45, s26
	v_lshl_add_u64 v[140:141], v[140:141], 0, s[46:47]
	s_mov_b32 m0, s10
	ds_read_b128 v[178:181], v144 offset:49152
	ds_read_b128 v[182:185], v144 offset:50176
	ds_read_b128 v[186:189], v144 offset:51200
	ds_read_b128 v[190:193], v144 offset:52224
	ds_read_b128 v[194:197], v144 offset:53248
	ds_read_b128 v[198:201], v144 offset:54272
	ds_read_b128 v[202:205], v144 offset:55296
	ds_read_b128 v[206:209], v144 offset:56320
	global_load_lds_dwordx4 v[140:141], off
	v_lshl_add_u64 v[140:141], v[212:213], 0, s[46:47]
	s_add_i32 m0, s10, 0x2000
	s_add_i32 s10, s52, s26
	global_load_lds_dwordx4 v[140:141], off
	v_lshl_add_u64 v[140:141], v[214:215], 0, s[46:47]
	s_mov_b32 m0, s10
	s_nop 0
	global_load_lds_dwordx4 v[140:141], off
	v_lshl_add_u64 v[140:141], v[216:217], 0, s[46:47]
	s_add_i32 m0, s10, 0x2000
	s_nop 0
	global_load_lds_dwordx4 v[140:141], off
	v_lshl_add_u64 v[140:141], v[218:219], 0, s[46:47]
	s_mov_b32 m0, s34
	s_nop 0
	global_load_lds_dwordx4 v[140:141], off
	v_lshl_add_u64 v[140:141], v[220:221], 0, s[46:47]
	s_mov_b32 m0, s35
	s_nop 0
	global_load_lds_dwordx4 v[140:141], off
	s_waitcnt vmcnt(8)
	s_waitcnt lgkmcnt(0)
	s_barrier
	s_setprio 1
	s_waitcnt lgkmcnt(0)
	v_mfma_f32_16x16x32_bf16 v[60:63], v[146:149], v[178:181], v[60:63]
	v_mfma_f32_16x16x32_bf16 v[56:59], v[154:157], v[178:181], v[56:59]
	v_mfma_f32_16x16x32_bf16 v[48:51], v[146:149], v[186:189], v[48:51]
	v_mfma_f32_16x16x32_bf16 v[40:43], v[154:157], v[186:189], v[40:43]
	v_mfma_f32_16x16x32_bf16 v[32:35], v[146:149], v[194:197], v[32:35]
	v_mfma_f32_16x16x32_bf16 v[24:27], v[154:157], v[194:197], v[24:27]
	v_mfma_f32_16x16x32_bf16 v[16:19], v[146:149], v[202:205], v[16:19]
	v_mfma_f32_16x16x32_bf16 v[8:11], v[154:157], v[202:205], v[8:11]
	v_mfma_f32_16x16x32_bf16 v[60:63], v[150:153], v[182:185], v[60:63]
	v_mfma_f32_16x16x32_bf16 v[56:59], v[158:161], v[182:185], v[56:59]
	v_mfma_f32_16x16x32_bf16 v[48:51], v[150:153], v[190:193], v[48:51]
	v_mfma_f32_16x16x32_bf16 v[40:43], v[158:161], v[190:193], v[40:43]
	v_mfma_f32_16x16x32_bf16 v[32:35], v[150:153], v[198:201], v[32:35]
	v_mfma_f32_16x16x32_bf16 v[24:27], v[158:161], v[198:201], v[24:27]
	v_mfma_f32_16x16x32_bf16 v[16:19], v[150:153], v[206:209], v[16:19]
	v_mfma_f32_16x16x32_bf16 v[8:11], v[158:161], v[206:209], v[8:11]
	v_mfma_f32_16x16x32_bf16 v[52:55], v[162:165], v[178:181], v[52:55]
	v_mfma_f32_16x16x32_bf16 v[44:47], v[170:173], v[178:181], v[44:47]
	v_mfma_f32_16x16x32_bf16 v[36:39], v[162:165], v[186:189], v[36:39]
	v_mfma_f32_16x16x32_bf16 v[28:31], v[170:173], v[186:189], v[28:31]
	v_mfma_f32_16x16x32_bf16 v[20:23], v[162:165], v[194:197], v[20:23]
	v_mfma_f32_16x16x32_bf16 v[12:15], v[170:173], v[194:197], v[12:15]
	v_mfma_f32_16x16x32_bf16 v[4:7], v[162:165], v[202:205], v[4:7]
	v_mfma_f32_16x16x32_bf16 v[0:3], v[170:173], v[202:205], v[0:3]
	v_mfma_f32_16x16x32_bf16 v[52:55], v[166:169], v[182:185], v[52:55]
	v_mfma_f32_16x16x32_bf16 v[44:47], v[174:177], v[182:185], v[44:47]
	v_mfma_f32_16x16x32_bf16 v[36:39], v[166:169], v[190:193], v[36:39]
	v_mfma_f32_16x16x32_bf16 v[28:31], v[174:177], v[190:193], v[28:31]
	v_mfma_f32_16x16x32_bf16 v[20:23], v[166:169], v[198:201], v[20:23]
	v_mfma_f32_16x16x32_bf16 v[12:15], v[174:177], v[198:201], v[12:15]
	v_mfma_f32_16x16x32_bf16 v[4:7], v[166:169], v[206:209], v[4:7]
	v_mfma_f32_16x16x32_bf16 v[0:3], v[174:177], v[206:209], v[0:3]
	s_setprio 0
	s_barrier
	s_add_u32 s24, s24, 0x100
	s_addc_u32 s25, s25, 0
	s_add_u32 s12, s12, 0x100
	s_addc_u32 s13, s13, 0
	s_cmp_ge_u32 s44, s31
	s_mov_b32 s10, s44
	s_cbranch_scc0 .LBB0_81
	s_and_b64 vcc, exec, s[20:21]
	s_cbranch_vccz .LBB0_84
	s_barrier

; #define PG8_STAGE(bufoff, gbase, voff) do { _Pragma("unroll") for (int _i = 0; _i < 2; ++_i) \
;         __builtin_amdgcn_global_load_lds((const unsigned*)((const char*)(gbase) + (voff)[_i]), (LAS unsigned*)(lds + (bufoff) + ldsw + _i * 8192), 16, 0, 0); } while (0)
; #define PG8_LDA(dst, b, h) do { _Pragma("unroll") for (int m = 0; m < 4; ++m) _Pragma("unroll") for (int k = 0; k < 2; ++k) dst[m][k] = *(const LAS bf16x8*)(lds + PG8_SA(b, h) + aoff + m * 2048 + k * 1024); } while (0)
; #define PG8_LDB(dst, b, h) do { _Pragma("unroll") for (int n = 0; n < 2; ++n) _Pragma("unroll") for (int k = 0; k < 2; ++k) dst[n][k] = *(const LAS bf16x8*)(lds + PG8_SB(b, h) + boff + n * 2048 + k * 1024); } while (0)
; #define PG8_MMA(ai, bj, At, Bt) do { __builtin_amdgcn_s_setprio(1); _Pragma("unroll") for (int m = 0; m < 4; ++m) _Pragma("unroll") for (int n = 0; n < 2; ++n) _Pragma("unroll") for (int k = 0; k < 2; ++k) \
;         acc[ai][bj][m][n] = __builtin_amdgcn_mfma_f32_16x16x32_bf16(Bt[n][k], At[m][k], acc[ai][bj][m][n], 0, 0, 0); __builtin_amdgcn_s_setprio(0); } while (0)
; #define PG8_WAIT_V(n) asm volatile("s_waitcnt vmcnt(" #n ")" ::: "memory")
; #define PG8_WAIT_L(n) asm volatile("s_waitcnt lgkmcnt(" #n ")" ::: "memory")
; #define PG8_BAR __builtin_amdgcn_s_barrier()
; template <class Epi, class Sched>
; __device__ __forceinline__ void gemm_phase(LAS unsigned char* lds, const Gemm g, const Sched& S, const Epi& E, const int wv) {
;     ...
;         for (int t = 0; t < nt; t += 2) {
;             const bool last = (t == nt - 2);
;             const char* a1 = cA + (size_t)(t + 1) * kstep;
;             const char* a2 = last ? nA : cA + (size_t)(t + 2) * kstep; const char* b2 = last ? nB : cB + (size_t)(t + 2) * kstep;
;             const char* a3 = a2 + kstep; const char* b3 = b2 + kstep;
;             if (last && has_next) S.a_ready(nxt);
;             PG8_LDB(B0, 0, 0); PG8_LDB(B1, 0, 1); PG8_SCHED; PG8_LDA(At, 0, 0); PG8_STAGE(PG8_SA(1, 1), a1 + hstep, voffA);
;             PG8_WAIT_V(8); PG8_WAIT_L(0); PG8_BAR; PG8_MMA(0, 0, At, B0); PG8_MMA(0, 1, At, B1); PG8_BAR; PG8_SCHED;
;             PG8_LDA(At, 0, 1); PG8_STAGE(PG8_SB(0, 0), b2, voffB); PG8_STAGE(PG8_SB(0, 1), b2 + hstep, voffB); PG8_STAGE(PG8_SA(0, 0), a2, voffA);
;             PG8_WAIT_V(8); PG8_WAIT_L(0); PG8_BAR; PG8_MMA(1, 0, At, B0); PG8_MMA(1, 1, At, B1); PG8_BAR; PG8_SCHED;
.LBB0_324:
	s_add_u32 s10, s22, 0xfff80080
	s_addc_u32 s11, s23, -1
	s_add_i32 s43, 0, 0x10000
	s_cmp_eq_u32 s42, 28
	s_cselect_b32 s13, s17, s11
	s_cselect_b32 s12, s37, s10
	v_add_u32_e32 v138, s43, v144
	s_cselect_b32 s11, s15, s41
	s_cselect_b32 s10, s38, s40
	s_add_i32 s52, 0, 0x14000
	ds_read_b128 v[140:143], v138
	ds_read_b128 v[148:151], v138 offset:1024
	ds_read_b128 v[152:155], v138 offset:2048
	ds_read_b128 v[156:159], v138 offset:3072
	v_add_u32_e32 v138, s52, v144
	ds_read_b128 v[160:163], v138
	ds_read_b128 v[164:167], v138 offset:1024
	ds_read_b128 v[168:171], v138 offset:2048
	ds_read_b128 v[172:175], v138 offset:3072
	v_lshl_add_u64 v[208:209], s[22:23], 0, v[134:135]
	s_add_i32 m0, s26, 0xc000
	ds_read_b128 v[176:179], v146
	ds_read_b128 v[180:183], v146 offset:1024
	ds_read_b128 v[184:187], v146 offset:2048
	ds_read_b128 v[188:191], v146 offset:3072
	ds_read_b128 v[192:195], v146 offset:4096
	ds_read_b128 v[196:199], v146 offset:5120
	ds_read_b128 v[200:203], v146 offset:6144
	ds_read_b128 v[204:207], v146 offset:7168
	global_load_lds_dwordx4 v[208:209], off
	v_lshl_add_u64 v[208:209], s[22:23], 0, v[136:137]
	s_add_i32 m0, s26, 0xe000
	s_nop 0
	global_load_lds_dwordx4 v[208:209], off
	s_waitcnt vmcnt(8)
	s_waitcnt lgkmcnt(0)
	s_barrier
	s_setprio 1
	s_waitcnt lgkmcnt(0)
	v_mfma_f32_16x16x32_bf16 v[124:127], v[140:143], v[176:179], v[124:127]
	v_mfma_f32_16x16x32_bf16 v[120:123], v[152:155], v[176:179], v[120:123]
	v_mfma_f32_16x16x32_bf16 v[112:115], v[140:143], v[184:187], v[112:115]
	v_mfma_f32_16x16x32_bf16 v[104:107], v[152:155], v[184:187], v[104:107]
	v_mfma_f32_16x16x32_bf16 v[96:99], v[140:143], v[192:195], v[96:99]
	v_mfma_f32_16x16x32_bf16 v[88:91], v[152:155], v[192:195], v[88:91]
	v_mfma_f32_16x16x32_bf16 v[80:83], v[140:143], v[200:203], v[80:83]
	v_mfma_f32_16x16x32_bf16 v[72:75], v[152:155], v[200:203], v[72:75]
	v_mfma_f32_16x16x32_bf16 v[124:127], v[148:151], v[180:183], v[124:127]
	v_mfma_f32_16x16x32_bf16 v[120:123], v[156:159], v[180:183], v[120:123]
	v_mfma_f32_16x16x32_bf16 v[112:115], v[148:151], v[188:191], v[112:115]
	v_mfma_f32_16x16x32_bf16 v[104:107], v[156:159], v[188:191], v[104:107]
	v_mfma_f32_16x16x32_bf16 v[96:99], v[148:151], v[196:199], v[96:99]
	v_mfma_f32_16x16x32_bf16 v[88:91], v[156:159], v[196:199], v[88:91]
	v_mfma_f32_16x16x32_bf16 v[80:83], v[148:151], v[204:207], v[80:83]
	v_mfma_f32_16x16x32_bf16 v[72:75], v[156:159], v[204:207], v[72:75]
	v_mfma_f32_16x16x32_bf16 v[116:119], v[160:163], v[176:179], v[116:119]
	v_mfma_f32_16x16x32_bf16 v[108:111], v[168:171], v[176:179], v[108:111]
	v_mfma_f32_16x16x32_bf16 v[100:103], v[160:163], v[184:187], v[100:103]
	v_mfma_f32_16x16x32_bf16 v[92:95], v[168:171], v[184:187], v[92:95]
	v_mfma_f32_16x16x32_bf16 v[84:87], v[160:163], v[192:195], v[84:87]
	v_mfma_f32_16x16x32_bf16 v[76:79], v[168:171], v[192:195], v[76:79]
	v_mfma_f32_16x16x32_bf16 v[68:71], v[160:163], v[200:203], v[68:71]
	v_mfma_f32_16x16x32_bf16 v[64:67], v[168:171], v[200:203], v[64:67]
	v_mfma_f32_16x16x32_bf16 v[116:119], v[164:167], v[180:183], v[116:119]
	v_mfma_f32_16x16x32_bf16 v[108:111], v[172:175], v[180:183], v[108:111]
	v_mfma_f32_16x16x32_bf16 v[100:103], v[164:167], v[188:191], v[100:103]
	v_mfma_f32_16x16x32_bf16 v[92:95], v[172:175], v[188:191], v[92:95]
	v_mfma_f32_16x16x32_bf16 v[84:87], v[164:167], v[196:199], v[84:87]
	v_mfma_f32_16x16x32_bf16 v[76:79], v[172:175], v[196:199], v[76:79]
	v_mfma_f32_16x16x32_bf16 v[68:71], v[164:167], v[204:207], v[68:71]
	v_mfma_f32_16x16x32_bf16 v[64:67], v[172:175], v[204:207], v[64:67]
	s_setprio 0
	s_barrier
	s_add_i32 s43, s43, s25
	v_lshl_add_u64 v[208:209], s[10:11], 0, v[210:211]
	s_mov_b32 m0, s43
	ds_read_b128 v[176:179], v146 offset:16384
	ds_read_b128 v[180:183], v146 offset:17408
	ds_read_b128 v[184:187], v146 offset:18432
	ds_read_b128 v[188:191], v146 offset:19456
	ds_read_b128 v[192:195], v146 offset:20480
	ds_read_b128 v[196:199], v146 offset:21504
	ds_read_b128 v[200:203], v146 offset:22528
	ds_read_b128 v[204:207], v146 offset:23552
	global_load_lds_dwordx4 v[208:209], off
	s_add_i32 m0, s43, 0x2000
	s_add_u32 s44, s10, 0x80000
	v_lshl_add_u64 v[212:213], s[10:11], 0, v[128:129]
	s_addc_u32 s45, s11, 0
	s_add_i32 s43, s52, s25
	global_load_lds_dwordx4 v[212:213], off
	v_lshl_add_u64 v[214:215], s[44:45], 0, v[210:211]
	s_mov_b32 m0, s43
	v_lshl_add_u64 v[216:217], s[12:13], 0, v[130:131]
	global_load_lds_dwordx4 v[214:215], off
	v_lshl_add_u64 v[214:215], s[44:45], 0, v[128:129]
	s_add_i32 m0, s43, 0x2000
	s_nop 0
	global_load_lds_dwordx4 v[214:215], off
	v_lshl_add_u64 v[214:215], s[12:13], 0, v[132:133]
	s_mov_b32 m0, s26
	s_nop 0
	global_load_lds_dwordx4 v[214:215], off
	s_mov_b32 m0, s27
	s_nop 0
	global_load_lds_dwordx4 v[216:217], off
	s_waitcnt vmcnt(8)
	s_waitcnt lgkmcnt(0)
	s_barrier
; #define PG8_STAGE(bufoff, gbase, voff) do { _Pragma("unroll") for (int _i = 0; _i < 2; ++_i) \
;         __builtin_amdgcn_global_load_lds((const unsigned*)((const char*)(gbase) + (voff)[_i]), (LAS unsigned*)(lds + (bufoff) + ldsw + _i * 8192), 16, 0, 0); } while (0)
; #define PG8_LDA(dst, b, h) do { _Pragma("unroll") for (int m = 0; m < 4; ++m) _Pragma("unroll") for (int k = 0; k < 2; ++k) dst[m][k] = *(const LAS bf16x8*)(lds + PG8_SA(b, h) + aoff + m * 2048 + k * 1024); } while (0)
; #define PG8_LDB(dst, b, h) do { _Pragma("unroll") for (int n = 0; n < 2; ++n) _Pragma("unroll") for (int k = 0; k < 2; ++k) dst[n][k] = *(const LAS bf16x8*)(lds + PG8_SB(b, h) + boff + n * 2048 + k * 1024); } while (0)
; #define PG8_MMA(ai, bj, At, Bt) do { __builtin_amdgcn_s_setprio(1); _Pragma("unroll") for (int m = 0; m < 4; ++m) _Pragma("unroll") for (int n = 0; n < 2; ++n) _Pragma("unroll") for (int k = 0; k < 2; ++k) \
;         acc[ai][bj][m][n] = __builtin_amdgcn_mfma_f32_16x16x32_bf16(Bt[n][k], At[m][k], acc[ai][bj][m][n], 0, 0, 0); __builtin_amdgcn_s_setprio(0); } while (0)
; #define PG8_WAIT_V(n) asm volatile("s_waitcnt vmcnt(" #n ")" ::: "memory")
; #define PG8_WAIT_L(n) asm volatile("s_waitcnt lgkmcnt(" #n ")" ::: "memory")
; #define PG8_BAR __builtin_amdgcn_s_barrier()
; #define PG8_SCHED __builtin_amdgcn_sched_barrier(0)
; template <class Epi, class Sched>
; __device__ __forceinline__ void gemm_phase(LAS unsigned char* lds, const Gemm g, const Sched& S, const Epi& E, const int wv) {
;     ...
;             PG8_WAIT_V(8); PG8_WAIT_L(0); PG8_BAR; PG8_MMA(1, 0, At, B0); PG8_MMA(1, 1, At, B1); PG8_BAR; PG8_SCHED;
;             PG8_LDB(B0, 1, 0); PG8_LDB(B1, 1, 1); PG8_SCHED; PG8_LDA(At, 1, 0); PG8_STAGE(PG8_SA(0, 1), a2 + hstep, voffA);
;             PG8_WAIT_V(8); PG8_WAIT_L(0); PG8_BAR; PG8_MMA(0, 0, At, B0); PG8_MMA(0, 1, At, B1); PG8_BAR; PG8_SCHED;
	s_setprio 1
	s_waitcnt lgkmcnt(0)
	v_mfma_f32_16x16x32_bf16 v[60:63], v[140:143], v[176:179], v[60:63]
	v_mfma_f32_16x16x32_bf16 v[56:59], v[152:155], v[176:179], v[56:59]
	v_mfma_f32_16x16x32_bf16 v[48:51], v[140:143], v[184:187], v[48:51]
	v_mfma_f32_16x16x32_bf16 v[40:43], v[152:155], v[184:187], v[40:43]
	v_mfma_f32_16x16x32_bf16 v[32:35], v[140:143], v[192:195], v[32:35]
	v_mfma_f32_16x16x32_bf16 v[24:27], v[152:155], v[192:195], v[24:27]
	v_mfma_f32_16x16x32_bf16 v[16:19], v[140:143], v[200:203], v[16:19]
	v_mfma_f32_16x16x32_bf16 v[8:11], v[152:155], v[200:203], v[8:11]
	v_mfma_f32_16x16x32_bf16 v[60:63], v[148:151], v[180:183], v[60:63]
	v_mfma_f32_16x16x32_bf16 v[56:59], v[156:159], v[180:183], v[56:59]
	v_mfma_f32_16x16x32_bf16 v[48:51], v[148:151], v[188:191], v[48:51]
	v_mfma_f32_16x16x32_bf16 v[40:43], v[156:159], v[188:191], v[40:43]
	v_mfma_f32_16x16x32_bf16 v[32:35], v[148:151], v[196:199], v[32:35]
	v_mfma_f32_16x16x32_bf16 v[24:27], v[156:159], v[196:199], v[24:27]
	v_mfma_f32_16x16x32_bf16 v[16:19], v[148:151], v[204:207], v[16:19]
	v_mfma_f32_16x16x32_bf16 v[8:11], v[156:159], v[204:207], v[8:11]
	v_mfma_f32_16x16x32_bf16 v[52:55], v[160:163], v[176:179], v[52:55]
	v_mfma_f32_16x16x32_bf16 v[44:47], v[168:171], v[176:179], v[44:47]
	v_mfma_f32_16x16x32_bf16 v[36:39], v[160:163], v[184:187], v[36:39]
	v_mfma_f32_16x16x32_bf16 v[28:31], v[168:171], v[184:187], v[28:31]
	v_mfma_f32_16x16x32_bf16 v[20:23], v[160:163], v[192:195], v[20:23]
	v_mfma_f32_16x16x32_bf16 v[12:15], v[168:171], v[192:195], v[12:15]
	v_mfma_f32_16x16x32_bf16 v[4:7], v[160:163], v[200:203], v[4:7]
	v_mfma_f32_16x16x32_bf16 v[0:3], v[168:171], v[200:203], v[0:3]
	v_mfma_f32_16x16x32_bf16 v[52:55], v[164:167], v[180:183], v[52:55]
	v_mfma_f32_16x16x32_bf16 v[44:47], v[172:175], v[180:183], v[44:47]
	v_mfma_f32_16x16x32_bf16 v[36:39], v[164:167], v[188:191], v[36:39]
	v_mfma_f32_16x16x32_bf16 v[28:31], v[172:175], v[188:191], v[28:31]
	v_mfma_f32_16x16x32_bf16 v[20:23], v[164:167], v[196:199], v[20:23]
	v_mfma_f32_16x16x32_bf16 v[12:15], v[172:175], v[196:199], v[12:15]
	v_mfma_f32_16x16x32_bf16 v[4:7], v[164:167], v[204:207], v[4:7]
	v_mfma_f32_16x16x32_bf16 v[0:3], v[172:175], v[204:207], v[0:3]
	s_setprio 0
	s_barrier
	s_add_i32 s43, 0, 0x18000
	v_add_u32_e32 v138, s43, v144
	s_add_i32 s44, 0, 0x1c000
	ds_read_b128 v[140:143], v138
	ds_read_b128 v[148:151], v138 offset:1024
	ds_read_b128 v[152:155], v138 offset:2048
	ds_read_b128 v[156:159], v138 offset:3072
	v_add_u32_e32 v138, s44, v144
	ds_read_b128 v[160:163], v138
	ds_read_b128 v[164:167], v138 offset:1024
	ds_read_b128 v[168:171], v138 offset:2048
	ds_read_b128 v[172:175], v138 offset:3072
	s_add_u32 s12, s12, 0x80000
	s_addc_u32 s13, s13, 0
	s_mov_b32 m0, s28
	v_lshl_add_u64 v[218:219], s[12:13], 0, v[132:133]
	ds_read_b128 v[176:179], v146 offset:32768
	ds_read_b128 v[180:183], v146 offset:33792
	ds_read_b128 v[184:187], v146 offset:34816
	ds_read_b128 v[188:191], v146 offset:35840
	ds_read_b128 v[192:195], v146 offset:36864
	ds_read_b128 v[196:199], v146 offset:37888
	ds_read_b128 v[200:203], v146 offset:38912
	ds_read_b128 v[204:207], v146 offset:39936
	global_load_lds_dwordx4 v[218:219], off
	v_lshl_add_u64 v[218:219], s[12:13], 0, v[130:131]
	s_mov_b32 m0, s29
	s_nop 0
	global_load_lds_dwordx4 v[218:219], off
	s_waitcnt vmcnt(8)
	s_waitcnt lgkmcnt(0)
	s_barrier
	s_setprio 1
	s_waitcnt lgkmcnt(0)
	v_mfma_f32_16x16x32_bf16 v[124:127], v[140:143], v[176:179], v[124:127]
	v_mfma_f32_16x16x32_bf16 v[120:123], v[152:155], v[176:179], v[120:123]
	v_mfma_f32_16x16x32_bf16 v[112:115], v[140:143], v[184:187], v[112:115]
	v_mfma_f32_16x16x32_bf16 v[104:107], v[152:155], v[184:187], v[104:107]
	v_mfma_f32_16x16x32_bf16 v[96:99], v[140:143], v[192:195], v[96:99]
	v_mfma_f32_16x16x32_bf16 v[88:91], v[152:155], v[192:195], v[88:91]
	v_mfma_f32_16x16x32_bf16 v[80:83], v[140:143], v[200:203], v[80:83]
	v_mfma_f32_16x16x32_bf16 v[72:75], v[152:155], v[200:203], v[72:75]
	v_mfma_f32_16x16x32_bf16 v[124:127], v[148:151], v[180:183], v[124:127]
	v_mfma_f32_16x16x32_bf16 v[120:123], v[156:159], v[180:183], v[120:123]
	v_mfma_f32_16x16x32_bf16 v[112:115], v[148:151], v[188:191], v[112:115]
	v_mfma_f32_16x16x32_bf16 v[104:107], v[156:159], v[188:191], v[104:107]
	v_mfma_f32_16x16x32_bf16 v[96:99], v[148:151], v[196:199], v[96:99]
	v_mfma_f32_16x16x32_bf16 v[88:91], v[156:159], v[196:199], v[88:91]
	v_mfma_f32_16x16x32_bf16 v[80:83], v[148:151], v[204:207], v[80:83]
	v_mfma_f32_16x16x32_bf16 v[72:75], v[156:159], v[204:207], v[72:75]
	v_mfma_f32_16x16x32_bf16 v[116:119], v[160:163], v[176:179], v[116:119]
	v_mfma_f32_16x16x32_bf16 v[108:111], v[168:171], v[176:179], v[108:111]
	v_mfma_f32_16x16x32_bf16 v[100:103], v[160:163], v[184:187], v[100:103]
	v_mfma_f32_16x16x32_bf16 v[92:95], v[168:171], v[184:187], v[92:95]
	v_mfma_f32_16x16x32_bf16 v[84:87], v[160:163], v[192:195], v[84:87]
	v_mfma_f32_16x16x32_bf16 v[76:79], v[168:171], v[192:195], v[76:79]
	v_mfma_f32_16x16x32_bf16 v[68:71], v[160:163], v[200:203], v[68:71]
	v_mfma_f32_16x16x32_bf16 v[64:67], v[168:171], v[200:203], v[64:67]
	v_mfma_f32_16x16x32_bf16 v[116:119], v[164:167], v[180:183], v[116:119]
	v_mfma_f32_16x16x32_bf16 v[108:111], v[172:175], v[180:183], v[108:111]
	v_mfma_f32_16x16x32_bf16 v[100:103], v[164:167], v[188:191], v[100:103]
	v_mfma_f32_16x16x32_bf16 v[92:95], v[172:175], v[188:191], v[92:95]
	v_mfma_f32_16x16x32_bf16 v[84:87], v[164:167], v[196:199], v[84:87]
	v_mfma_f32_16x16x32_bf16 v[76:79], v[172:175], v[196:199], v[76:79]
	v_mfma_f32_16x16x32_bf16 v[68:71], v[164:167], v[204:207], v[68:71]
	v_mfma_f32_16x16x32_bf16 v[64:67], v[172:175], v[204:207], v[64:67]
	s_setprio 0
	s_barrier
; #define PG8_STAGE(bufoff, gbase, voff) do { _Pragma("unroll") for (int _i = 0; _i < 2; ++_i) \
;         __builtin_amdgcn_global_load_lds((const unsigned*)((const char*)(gbase) + (voff)[_i]), (LAS unsigned*)(lds + (bufoff) + ldsw + _i * 8192), 16, 0, 0); } while (0)
; #define PG8_LDA(dst, b, h) do { _Pragma("unroll") for (int m = 0; m < 4; ++m) _Pragma("unroll") for (int k = 0; k < 2; ++k) dst[m][k] = *(const LAS bf16x8*)(lds + PG8_SA(b, h) + aoff + m * 2048 + k * 1024); } while (0)
; #define PG8_MMA(ai, bj, At, Bt) do { __builtin_amdgcn_s_setprio(1); _Pragma("unroll") for (int m = 0; m < 4; ++m) _Pragma("unroll") for (int n = 0; n < 2; ++n) _Pragma("unroll") for (int k = 0; k < 2; ++k) \
;         acc[ai][bj][m][n] = __builtin_amdgcn_mfma_f32_16x16x32_bf16(Bt[n][k], At[m][k], acc[ai][bj][m][n], 0, 0, 0); __builtin_amdgcn_s_setprio(0); } while (0)
; #define PG8_WAIT_V(n) asm volatile("s_waitcnt vmcnt(" #n ")" ::: "memory")
; #define PG8_WAIT_L(n) asm volatile("s_waitcnt lgkmcnt(" #n ")" ::: "memory")
; #define PG8_BAR __builtin_amdgcn_s_barrier()
; #define PG8_SCHED __builtin_amdgcn_sched_barrier(0)
; template <class Epi, class Sched>
; __device__ __forceinline__ void gemm_phase(LAS unsigned char* lds, const Gemm g, const Sched& S, const Epi& E, const int wv) {
;     ...
;             PG8_LDA(At, 1, 1); PG8_STAGE(PG8_SB(1, 0), b3, voffB); PG8_STAGE(PG8_SB(1, 1), b3 + hstep, voffB); PG8_STAGE(PG8_SA(1, 0), a3, voffA);
;             PG8_WAIT_V(8); PG8_WAIT_L(0); PG8_BAR; PG8_MMA(1, 0, At, B0); PG8_MMA(1, 1, At, B1); PG8_BAR; PG8_SCHED;
;         }
;         if (wr == 0) PG8_BAR;
	s_add_i32 s12, s43, s25
	v_lshl_add_u64 v[208:209], v[208:209], 0, s[46:47]
	s_mov_b32 m0, s12
	ds_read_b128 v[176:179], v146 offset:49152
	ds_read_b128 v[180:183], v146 offset:50176
	ds_read_b128 v[184:187], v146 offset:51200
	ds_read_b128 v[188:191], v146 offset:52224
	ds_read_b128 v[192:195], v146 offset:53248
	ds_read_b128 v[196:199], v146 offset:54272
	ds_read_b128 v[200:203], v146 offset:55296
	ds_read_b128 v[204:207], v146 offset:56320
	global_load_lds_dwordx4 v[208:209], off
	s_add_i32 m0, s12, 0x2000
	s_add_u32 s10, s10, 0x80080
	v_lshl_add_u64 v[208:209], v[212:213], 0, s[46:47]
	s_addc_u32 s11, s11, 0
	s_add_i32 s12, s44, s25
	global_load_lds_dwordx4 v[208:209], off
	v_lshl_add_u64 v[208:209], s[10:11], 0, v[210:211]
	s_mov_b32 m0, s12
	s_nop 0
	global_load_lds_dwordx4 v[208:209], off
	v_lshl_add_u64 v[208:209], s[10:11], 0, v[128:129]
	s_add_i32 m0, s12, 0x2000
	s_nop 0
	global_load_lds_dwordx4 v[208:209], off
	v_lshl_add_u64 v[208:209], v[214:215], 0, s[46:47]
	s_mov_b32 m0, s30
	s_nop 0
	global_load_lds_dwordx4 v[208:209], off
	v_lshl_add_u64 v[208:209], v[216:217], 0, s[46:47]
	s_mov_b32 m0, s31
	s_nop 0
	global_load_lds_dwordx4 v[208:209], off
	s_waitcnt vmcnt(8)
	s_waitcnt lgkmcnt(0)
	s_barrier
	s_setprio 1
	s_waitcnt lgkmcnt(0)
	v_mfma_f32_16x16x32_bf16 v[60:63], v[140:143], v[176:179], v[60:63]
	v_mfma_f32_16x16x32_bf16 v[56:59], v[152:155], v[176:179], v[56:59]
	v_mfma_f32_16x16x32_bf16 v[48:51], v[140:143], v[184:187], v[48:51]
	v_mfma_f32_16x16x32_bf16 v[40:43], v[152:155], v[184:187], v[40:43]
	v_mfma_f32_16x16x32_bf16 v[32:35], v[140:143], v[192:195], v[32:35]
	v_mfma_f32_16x16x32_bf16 v[24:27], v[152:155], v[192:195], v[24:27]
	v_mfma_f32_16x16x32_bf16 v[16:19], v[140:143], v[200:203], v[16:19]
	v_mfma_f32_16x16x32_bf16 v[8:11], v[152:155], v[200:203], v[8:11]
	v_mfma_f32_16x16x32_bf16 v[60:63], v[148:151], v[180:183], v[60:63]
	v_mfma_f32_16x16x32_bf16 v[56:59], v[156:159], v[180:183], v[56:59]
	v_mfma_f32_16x16x32_bf16 v[48:51], v[148:151], v[188:191], v[48:51]
	v_mfma_f32_16x16x32_bf16 v[40:43], v[156:159], v[188:191], v[40:43]
	v_mfma_f32_16x16x32_bf16 v[32:35], v[148:151], v[196:199], v[32:35]
	v_mfma_f32_16x16x32_bf16 v[24:27], v[156:159], v[196:199], v[24:27]
	v_mfma_f32_16x16x32_bf16 v[16:19], v[148:151], v[204:207], v[16:19]
	v_mfma_f32_16x16x32_bf16 v[8:11], v[156:159], v[204:207], v[8:11]
	v_mfma_f32_16x16x32_bf16 v[52:55], v[160:163], v[176:179], v[52:55]
	v_mfma_f32_16x16x32_bf16 v[44:47], v[168:171], v[176:179], v[44:47]
	v_mfma_f32_16x16x32_bf16 v[36:39], v[160:163], v[184:187], v[36:39]
	v_mfma_f32_16x16x32_bf16 v[28:31], v[168:171], v[184:187], v[28:31]
	v_mfma_f32_16x16x32_bf16 v[20:23], v[160:163], v[192:195], v[20:23]
	v_mfma_f32_16x16x32_bf16 v[12:15], v[168:171], v[192:195], v[12:15]
	v_mfma_f32_16x16x32_bf16 v[4:7], v[160:163], v[200:203], v[4:7]
	v_mfma_f32_16x16x32_bf16 v[0:3], v[168:171], v[200:203], v[0:3]
	v_mfma_f32_16x16x32_bf16 v[52:55], v[164:167], v[180:183], v[52:55]
	v_mfma_f32_16x16x32_bf16 v[44:47], v[172:175], v[180:183], v[44:47]
	v_mfma_f32_16x16x32_bf16 v[36:39], v[164:167], v[188:191], v[36:39]
	v_mfma_f32_16x16x32_bf16 v[28:31], v[172:175], v[188:191], v[28:31]
	v_mfma_f32_16x16x32_bf16 v[20:23], v[164:167], v[196:199], v[20:23]
	v_mfma_f32_16x16x32_bf16 v[12:15], v[172:175], v[196:199], v[12:15]
	v_mfma_f32_16x16x32_bf16 v[4:7], v[164:167], v[204:207], v[4:7]
	v_mfma_f32_16x16x32_bf16 v[0:3], v[172:175], v[204:207], v[0:3]
	s_setprio 0
	s_barrier
	s_add_i32 s42, s42, 2
	s_add_u32 s22, s22, 0x100
	s_addc_u32 s23, s23, 0
	s_add_u32 s40, s40, 0x100
	s_addc_u32 s41, s41, 0
	s_cmp_gt_u32 s42, 29
	s_cbranch_scc0 .LBB0_324
	s_and_b64 vcc, exec, s[8:9]
	s_cbranch_vccz .LBB0_327
	s_barrier

; #define PG8_STAGE(bufoff, gbase, voff) do { _Pragma("unroll") for (int _i = 0; _i < 2; ++_i) \
;         __builtin_amdgcn_global_load_lds((const unsigned*)((const char*)(gbase) + (voff)[_i]), (LAS unsigned*)(lds + (bufoff) + ldsw + _i * 8192), 16, 0, 0); } while (0)
; #define PG8_LDA(dst, b, h) do { _Pragma("unroll") for (int m = 0; m < 4; ++m) _Pragma("unroll") for (int k = 0; k < 2; ++k) dst[m][k] = *(const LAS bf16x8*)(lds + PG8_SA(b, h) + aoff + m * 2048 + k * 1024); } while (0)
; #define PG8_LDB(dst, b, h) do { _Pragma("unroll") for (int n = 0; n < 2; ++n) _Pragma("unroll") for (int k = 0; k < 2; ++k) dst[n][k] = *(const LAS bf16x8*)(lds + PG8_SB(b, h) + boff + n * 2048 + k * 1024); } while (0)
; #define PG8_MMA(ai, bj, At, Bt) do { __builtin_amdgcn_s_setprio(1); _Pragma("unroll") for (int m = 0; m < 4; ++m) _Pragma("unroll") for (int n = 0; n < 2; ++n) _Pragma("unroll") for (int k = 0; k < 2; ++k) \
;         acc[ai][bj][m][n] = __builtin_amdgcn_mfma_f32_16x16x32_bf16(Bt[n][k], At[m][k], acc[ai][bj][m][n], 0, 0, 0); __builtin_amdgcn_s_setprio(0); } while (0)
; #define PG8_WAIT_V(n) asm volatile("s_waitcnt vmcnt(" #n ")" ::: "memory")
; #define PG8_WAIT_L(n) asm volatile("s_waitcnt lgkmcnt(" #n ")" ::: "memory")
; #define PG8_BAR __builtin_amdgcn_s_barrier()
; template <class Epi, class Sched>
; __device__ __forceinline__ void gemm_phase(LAS unsigned char* lds, const Gemm g, const Sched& S, const Epi& E, const int wv) {
;     ...
;         for (int t = 0; t < nt; t += 2) {
;             const bool last = (t == nt - 2);
;             const char* a1 = cA + (size_t)(t + 1) * kstep;
;             const char* a2 = last ? nA : cA + (size_t)(t + 2) * kstep; const char* b2 = last ? nB : cB + (size_t)(t + 2) * kstep;
;             const char* a3 = a2 + kstep; const char* b3 = b2 + kstep;
;             if (last && has_next) S.a_ready(nxt);
;             PG8_LDB(B0, 0, 0); PG8_LDB(B1, 0, 1); PG8_SCHED; PG8_LDA(At, 0, 0); PG8_STAGE(PG8_SA(1, 1), a1 + hstep, voffA);
;             PG8_WAIT_V(8); PG8_WAIT_L(0); PG8_BAR; PG8_MMA(0, 0, At, B0); PG8_MMA(0, 1, At, B1); PG8_BAR; PG8_SCHED;
;             PG8_LDA(At, 0, 1); PG8_STAGE(PG8_SB(0, 0), b2, voffB); PG8_STAGE(PG8_SB(0, 1), b2 + hstep, voffB); PG8_STAGE(PG8_SA(0, 0), a2, voffA);
;             PG8_WAIT_V(8); PG8_WAIT_L(0); PG8_BAR; PG8_MMA(1, 0, At, B0); PG8_MMA(1, 1, At, B1); PG8_BAR; PG8_SCHED;
.LBB0_346:
	s_add_u32 s10, s16, 0xfff80080
	s_addc_u32 s11, s17, -1
	s_add_i32 s43, 0, 0x10000
	s_cmp_eq_u32 s42, 28
	s_cselect_b32 s13, s19, s11
	s_cselect_b32 s12, s37, s10
	v_add_u32_e32 v152, s43, v155
	s_cselect_b32 s11, s15, s41
	s_cselect_b32 s10, s38, s40
	s_add_i32 s52, 0, 0x14000
	ds_read_b128 v[140:143], v152
	ds_read_b128 v[144:147], v152 offset:1024
	ds_read_b128 v[148:151], v152 offset:2048
	ds_read_b128 v[158:161], v152 offset:3072
	v_add_u32_e32 v152, s52, v155
	ds_read_b128 v[162:165], v152
	ds_read_b128 v[166:169], v152 offset:1024
	ds_read_b128 v[170:173], v152 offset:2048
	ds_read_b128 v[174:177], v152 offset:3072
	v_lshl_add_u64 v[152:153], s[16:17], 0, v[136:137]
	s_add_i32 m0, s26, 0xc000
	ds_read_b128 v[178:181], v157
	ds_read_b128 v[182:185], v157 offset:1024
	ds_read_b128 v[186:189], v157 offset:2048
	ds_read_b128 v[190:193], v157 offset:3072
	ds_read_b128 v[194:197], v157 offset:4096
	ds_read_b128 v[198:201], v157 offset:5120
	ds_read_b128 v[202:205], v157 offset:6144
	ds_read_b128 v[206:209], v157 offset:7168
	global_load_lds_dwordx4 v[152:153], off
	v_lshl_add_u64 v[152:153], s[16:17], 0, v[138:139]
	s_add_i32 m0, s26, 0xe000
	s_nop 0
	global_load_lds_dwordx4 v[152:153], off
	s_waitcnt vmcnt(8)
	s_waitcnt lgkmcnt(0)
	s_barrier
	s_setprio 1
	s_waitcnt lgkmcnt(0)
	v_mfma_f32_16x16x32_bf16 v[124:127], v[140:143], v[178:181], v[124:127]
	v_mfma_f32_16x16x32_bf16 v[116:119], v[148:151], v[178:181], v[116:119]
	v_mfma_f32_16x16x32_bf16 v[108:111], v[140:143], v[186:189], v[108:111]
	v_mfma_f32_16x16x32_bf16 v[100:103], v[148:151], v[186:189], v[100:103]
	v_mfma_f32_16x16x32_bf16 v[92:95], v[140:143], v[194:197], v[92:95]
	v_mfma_f32_16x16x32_bf16 v[84:87], v[148:151], v[194:197], v[84:87]
	v_mfma_f32_16x16x32_bf16 v[76:79], v[140:143], v[202:205], v[76:79]
	v_mfma_f32_16x16x32_bf16 v[68:71], v[148:151], v[202:205], v[68:71]
	v_mfma_f32_16x16x32_bf16 v[124:127], v[144:147], v[182:185], v[124:127]
	v_mfma_f32_16x16x32_bf16 v[116:119], v[158:161], v[182:185], v[116:119]
	v_mfma_f32_16x16x32_bf16 v[108:111], v[144:147], v[190:193], v[108:111]
	v_mfma_f32_16x16x32_bf16 v[100:103], v[158:161], v[190:193], v[100:103]
	v_mfma_f32_16x16x32_bf16 v[92:95], v[144:147], v[198:201], v[92:95]
	v_mfma_f32_16x16x32_bf16 v[84:87], v[158:161], v[198:201], v[84:87]
	v_mfma_f32_16x16x32_bf16 v[76:79], v[144:147], v[206:209], v[76:79]
	v_mfma_f32_16x16x32_bf16 v[68:71], v[158:161], v[206:209], v[68:71]
	v_mfma_f32_16x16x32_bf16 v[120:123], v[162:165], v[178:181], v[120:123]
	v_mfma_f32_16x16x32_bf16 v[112:115], v[170:173], v[178:181], v[112:115]
	v_mfma_f32_16x16x32_bf16 v[104:107], v[162:165], v[186:189], v[104:107]
	v_mfma_f32_16x16x32_bf16 v[96:99], v[170:173], v[186:189], v[96:99]
	v_mfma_f32_16x16x32_bf16 v[88:91], v[162:165], v[194:197], v[88:91]
	v_mfma_f32_16x16x32_bf16 v[80:83], v[170:173], v[194:197], v[80:83]
	v_mfma_f32_16x16x32_bf16 v[72:75], v[162:165], v[202:205], v[72:75]
	v_mfma_f32_16x16x32_bf16 v[64:67], v[170:173], v[202:205], v[64:67]
	v_mfma_f32_16x16x32_bf16 v[120:123], v[166:169], v[182:185], v[120:123]
	v_mfma_f32_16x16x32_bf16 v[112:115], v[174:177], v[182:185], v[112:115]
	v_mfma_f32_16x16x32_bf16 v[104:107], v[166:169], v[190:193], v[104:107]
	v_mfma_f32_16x16x32_bf16 v[96:99], v[174:177], v[190:193], v[96:99]
	v_mfma_f32_16x16x32_bf16 v[88:91], v[166:169], v[198:201], v[88:91]
	v_mfma_f32_16x16x32_bf16 v[80:83], v[174:177], v[198:201], v[80:83]
	v_mfma_f32_16x16x32_bf16 v[72:75], v[166:169], v[206:209], v[72:75]
	v_mfma_f32_16x16x32_bf16 v[64:67], v[174:177], v[206:209], v[64:67]
	s_setprio 0
	s_barrier
	s_add_i32 s43, s43, s25
	v_lshl_add_u64 v[152:153], s[10:11], 0, v[132:133]
	s_mov_b32 m0, s43
	ds_read_b128 v[178:181], v157 offset:16384
	ds_read_b128 v[182:185], v157 offset:17408
	ds_read_b128 v[186:189], v157 offset:18432
	ds_read_b128 v[190:193], v157 offset:19456
	ds_read_b128 v[194:197], v157 offset:20480
	ds_read_b128 v[198:201], v157 offset:21504
	ds_read_b128 v[202:205], v157 offset:22528
	ds_read_b128 v[206:209], v157 offset:23552
	global_load_lds_dwordx4 v[152:153], off
	s_add_i32 m0, s43, 0x2000
	s_add_u32 s44, s10, 0x80000
	v_lshl_add_u64 v[212:213], s[10:11], 0, v[128:129]
	s_addc_u32 s45, s11, 0
	s_add_i32 s43, s52, s25
	global_load_lds_dwordx4 v[212:213], off
	v_lshl_add_u64 v[214:215], s[44:45], 0, v[132:133]
	s_mov_b32 m0, s43
	v_lshl_add_u64 v[216:217], s[12:13], 0, v[130:131]
	global_load_lds_dwordx4 v[214:215], off
	v_lshl_add_u64 v[214:215], s[44:45], 0, v[128:129]
	s_add_i32 m0, s43, 0x2000
	s_nop 0
	global_load_lds_dwordx4 v[214:215], off
	v_lshl_add_u64 v[214:215], s[12:13], 0, v[134:135]
	s_mov_b32 m0, s26
	s_nop 0
	global_load_lds_dwordx4 v[214:215], off
	s_mov_b32 m0, s27
	s_nop 0
	global_load_lds_dwordx4 v[216:217], off
	s_waitcnt vmcnt(8)
	s_waitcnt lgkmcnt(0)
	s_barrier
; #define PG8_STAGE(bufoff, gbase, voff) do { _Pragma("unroll") for (int _i = 0; _i < 2; ++_i) \
;         __builtin_amdgcn_global_load_lds((const unsigned*)((const char*)(gbase) + (voff)[_i]), (LAS unsigned*)(lds + (bufoff) + ldsw + _i * 8192), 16, 0, 0); } while (0)
; #define PG8_LDA(dst, b, h) do { _Pragma("unroll") for (int m = 0; m < 4; ++m) _Pragma("unroll") for (int k = 0; k < 2; ++k) dst[m][k] = *(const LAS bf16x8*)(lds + PG8_SA(b, h) + aoff + m * 2048 + k * 1024); } while (0)
; #define PG8_LDB(dst, b, h) do { _Pragma("unroll") for (int n = 0; n < 2; ++n) _Pragma("unroll") for (int k = 0; k < 2; ++k) dst[n][k] = *(const LAS bf16x8*)(lds + PG8_SB(b, h) + boff + n * 2048 + k * 1024); } while (0)
; #define PG8_MMA(ai, bj, At, Bt) do { __builtin_amdgcn_s_setprio(1); _Pragma("unroll") for (int m = 0; m < 4; ++m) _Pragma("unroll") for (int n = 0; n < 2; ++n) _Pragma("unroll") for (int k = 0; k < 2; ++k) \
;         acc[ai][bj][m][n] = __builtin_amdgcn_mfma_f32_16x16x32_bf16(Bt[n][k], At[m][k], acc[ai][bj][m][n], 0, 0, 0); __builtin_amdgcn_s_setprio(0); } while (0)
; #define PG8_WAIT_V(n) asm volatile("s_waitcnt vmcnt(" #n ")" ::: "memory")
; #define PG8_WAIT_L(n) asm volatile("s_waitcnt lgkmcnt(" #n ")" ::: "memory")
; #define PG8_BAR __builtin_amdgcn_s_barrier()
; #define PG8_SCHED __builtin_amdgcn_sched_barrier(0)
; template <class Epi, class Sched>
; __device__ __forceinline__ void gemm_phase(LAS unsigned char* lds, const Gemm g, const Sched& S, const Epi& E, const int wv) {
;     ...
;             PG8_WAIT_V(8); PG8_WAIT_L(0); PG8_BAR; PG8_MMA(1, 0, At, B0); PG8_MMA(1, 1, At, B1); PG8_BAR; PG8_SCHED;
;             PG8_LDB(B0, 1, 0); PG8_LDB(B1, 1, 1); PG8_SCHED; PG8_LDA(At, 1, 0); PG8_STAGE(PG8_SA(0, 1), a2 + hstep, voffA);
;             PG8_WAIT_V(8); PG8_WAIT_L(0); PG8_BAR; PG8_MMA(0, 0, At, B0); PG8_MMA(0, 1, At, B1); PG8_BAR; PG8_SCHED;
	s_setprio 1
	s_waitcnt lgkmcnt(0)
	v_mfma_f32_16x16x32_bf16 v[60:63], v[140:143], v[178:181], v[60:63]
	v_mfma_f32_16x16x32_bf16 v[52:55], v[148:151], v[178:181], v[52:55]
	v_mfma_f32_16x16x32_bf16 v[44:47], v[140:143], v[186:189], v[44:47]
	v_mfma_f32_16x16x32_bf16 v[36:39], v[148:151], v[186:189], v[36:39]
	v_mfma_f32_16x16x32_bf16 v[28:31], v[140:143], v[194:197], v[28:31]
	v_mfma_f32_16x16x32_bf16 v[20:23], v[148:151], v[194:197], v[20:23]
	v_mfma_f32_16x16x32_bf16 v[12:15], v[140:143], v[202:205], v[12:15]
	v_mfma_f32_16x16x32_bf16 v[4:7], v[148:151], v[202:205], v[4:7]
	v_mfma_f32_16x16x32_bf16 v[60:63], v[144:147], v[182:185], v[60:63]
	v_mfma_f32_16x16x32_bf16 v[52:55], v[158:161], v[182:185], v[52:55]
	v_mfma_f32_16x16x32_bf16 v[44:47], v[144:147], v[190:193], v[44:47]
	v_mfma_f32_16x16x32_bf16 v[36:39], v[158:161], v[190:193], v[36:39]
	v_mfma_f32_16x16x32_bf16 v[28:31], v[144:147], v[198:201], v[28:31]
	v_mfma_f32_16x16x32_bf16 v[20:23], v[158:161], v[198:201], v[20:23]
	v_mfma_f32_16x16x32_bf16 v[12:15], v[144:147], v[206:209], v[12:15]
	v_mfma_f32_16x16x32_bf16 v[4:7], v[158:161], v[206:209], v[4:7]
	v_mfma_f32_16x16x32_bf16 v[56:59], v[162:165], v[178:181], v[56:59]
	v_mfma_f32_16x16x32_bf16 v[48:51], v[170:173], v[178:181], v[48:51]
	v_mfma_f32_16x16x32_bf16 v[40:43], v[162:165], v[186:189], v[40:43]
	v_mfma_f32_16x16x32_bf16 v[32:35], v[170:173], v[186:189], v[32:35]
	v_mfma_f32_16x16x32_bf16 v[24:27], v[162:165], v[194:197], v[24:27]
	v_mfma_f32_16x16x32_bf16 v[16:19], v[170:173], v[194:197], v[16:19]
	v_mfma_f32_16x16x32_bf16 v[8:11], v[162:165], v[202:205], v[8:11]
	v_mfma_f32_16x16x32_bf16 v[0:3], v[170:173], v[202:205], v[0:3]
	v_mfma_f32_16x16x32_bf16 v[56:59], v[166:169], v[182:185], v[56:59]
	v_mfma_f32_16x16x32_bf16 v[48:51], v[174:177], v[182:185], v[48:51]
	v_mfma_f32_16x16x32_bf16 v[40:43], v[166:169], v[190:193], v[40:43]
	v_mfma_f32_16x16x32_bf16 v[32:35], v[174:177], v[190:193], v[32:35]
	v_mfma_f32_16x16x32_bf16 v[24:27], v[166:169], v[198:201], v[24:27]
	v_mfma_f32_16x16x32_bf16 v[16:19], v[174:177], v[198:201], v[16:19]
	v_mfma_f32_16x16x32_bf16 v[8:11], v[166:169], v[206:209], v[8:11]
	v_mfma_f32_16x16x32_bf16 v[0:3], v[174:177], v[206:209], v[0:3]
	s_setprio 0
	s_barrier
	s_add_i32 s43, 0, 0x18000
	s_add_i32 s44, 0, 0x1c000
	v_add_u32_e32 v158, s43, v155
	v_add_u32_e32 v174, s44, v155
	ds_read_b128 v[140:143], v158
	ds_read_b128 v[144:147], v158 offset:1024
	ds_read_b128 v[148:151], v158 offset:2048
	ds_read_b128 v[158:161], v158 offset:3072
	ds_read_b128 v[162:165], v174
	ds_read_b128 v[166:169], v174 offset:1024
	ds_read_b128 v[170:173], v174 offset:2048
	ds_read_b128 v[174:177], v174 offset:3072
	s_add_u32 s12, s12, 0x80000
	s_addc_u32 s13, s13, 0
	s_mov_b32 m0, s28
	v_lshl_add_u64 v[218:219], s[12:13], 0, v[134:135]
	ds_read_b128 v[178:181], v157 offset:32768
	ds_read_b128 v[182:185], v157 offset:33792
	ds_read_b128 v[186:189], v157 offset:34816
	ds_read_b128 v[190:193], v157 offset:35840
	ds_read_b128 v[194:197], v157 offset:36864
	ds_read_b128 v[198:201], v157 offset:37888
	ds_read_b128 v[202:205], v157 offset:38912
	ds_read_b128 v[206:209], v157 offset:39936
	global_load_lds_dwordx4 v[218:219], off
	v_lshl_add_u64 v[218:219], s[12:13], 0, v[130:131]
	s_mov_b32 m0, s29
	s_nop 0
	global_load_lds_dwordx4 v[218:219], off
	s_waitcnt vmcnt(8)
	s_waitcnt lgkmcnt(0)
	s_barrier
	s_setprio 1
	s_waitcnt lgkmcnt(0)
	v_mfma_f32_16x16x32_bf16 v[124:127], v[140:143], v[178:181], v[124:127]
	v_mfma_f32_16x16x32_bf16 v[116:119], v[148:151], v[178:181], v[116:119]
	v_mfma_f32_16x16x32_bf16 v[108:111], v[140:143], v[186:189], v[108:111]
	v_mfma_f32_16x16x32_bf16 v[100:103], v[148:151], v[186:189], v[100:103]
	v_mfma_f32_16x16x32_bf16 v[92:95], v[140:143], v[194:197], v[92:95]
	v_mfma_f32_16x16x32_bf16 v[84:87], v[148:151], v[194:197], v[84:87]
	v_mfma_f32_16x16x32_bf16 v[76:79], v[140:143], v[202:205], v[76:79]
	v_mfma_f32_16x16x32_bf16 v[68:71], v[148:151], v[202:205], v[68:71]
	v_mfma_f32_16x16x32_bf16 v[124:127], v[144:147], v[182:185], v[124:127]
	v_mfma_f32_16x16x32_bf16 v[116:119], v[158:161], v[182:185], v[116:119]
	v_mfma_f32_16x16x32_bf16 v[108:111], v[144:147], v[190:193], v[108:111]
	v_mfma_f32_16x16x32_bf16 v[100:103], v[158:161], v[190:193], v[100:103]
	v_mfma_f32_16x16x32_bf16 v[92:95], v[144:147], v[198:201], v[92:95]
	v_mfma_f32_16x16x32_bf16 v[84:87], v[158:161], v[198:201], v[84:87]
	v_mfma_f32_16x16x32_bf16 v[76:79], v[144:147], v[206:209], v[76:79]
	v_mfma_f32_16x16x32_bf16 v[68:71], v[158:161], v[206:209], v[68:71]
	v_mfma_f32_16x16x32_bf16 v[120:123], v[162:165], v[178:181], v[120:123]
	v_mfma_f32_16x16x32_bf16 v[112:115], v[170:173], v[178:181], v[112:115]
	v_mfma_f32_16x16x32_bf16 v[104:107], v[162:165], v[186:189], v[104:107]
	v_mfma_f32_16x16x32_bf16 v[96:99], v[170:173], v[186:189], v[96:99]
	v_mfma_f32_16x16x32_bf16 v[88:91], v[162:165], v[194:197], v[88:91]
	v_mfma_f32_16x16x32_bf16 v[80:83], v[170:173], v[194:197], v[80:83]
	v_mfma_f32_16x16x32_bf16 v[72:75], v[162:165], v[202:205], v[72:75]
	v_mfma_f32_16x16x32_bf16 v[64:67], v[170:173], v[202:205], v[64:67]
	v_mfma_f32_16x16x32_bf16 v[120:123], v[166:169], v[182:185], v[120:123]
	v_mfma_f32_16x16x32_bf16 v[112:115], v[174:177], v[182:185], v[112:115]
	v_mfma_f32_16x16x32_bf16 v[104:107], v[166:169], v[190:193], v[104:107]
	v_mfma_f32_16x16x32_bf16 v[96:99], v[174:177], v[190:193], v[96:99]
	v_mfma_f32_16x16x32_bf16 v[88:91], v[166:169], v[198:201], v[88:91]
	v_mfma_f32_16x16x32_bf16 v[80:83], v[174:177], v[198:201], v[80:83]
	v_mfma_f32_16x16x32_bf16 v[72:75], v[166:169], v[206:209], v[72:75]
	v_mfma_f32_16x16x32_bf16 v[64:67], v[174:177], v[206:209], v[64:67]
	s_setprio 0
	s_barrier
; #define PG8_STAGE(bufoff, gbase, voff) do { _Pragma("unroll") for (int _i = 0; _i < 2; ++_i) \
;         __builtin_amdgcn_global_load_lds((const unsigned*)((const char*)(gbase) + (voff)[_i]), (LAS unsigned*)(lds + (bufoff) + ldsw + _i * 8192), 16, 0, 0); } while (0)
; #define PG8_LDA(dst, b, h) do { _Pragma("unroll") for (int m = 0; m < 4; ++m) _Pragma("unroll") for (int k = 0; k < 2; ++k) dst[m][k] = *(const LAS bf16x8*)(lds + PG8_SA(b, h) + aoff + m * 2048 + k * 1024); } while (0)
; #define PG8_MMA(ai, bj, At, Bt) do { __builtin_amdgcn_s_setprio(1); _Pragma("unroll") for (int m = 0; m < 4; ++m) _Pragma("unroll") for (int n = 0; n < 2; ++n) _Pragma("unroll") for (int k = 0; k < 2; ++k) \
;         acc[ai][bj][m][n] = __builtin_amdgcn_mfma_f32_16x16x32_bf16(Bt[n][k], At[m][k], acc[ai][bj][m][n], 0, 0, 0); __builtin_amdgcn_s_setprio(0); } while (0)
; #define PG8_WAIT_V(n) asm volatile("s_waitcnt vmcnt(" #n ")" ::: "memory")
; #define PG8_WAIT_L(n) asm volatile("s_waitcnt lgkmcnt(" #n ")" ::: "memory")
; #define PG8_BAR __builtin_amdgcn_s_barrier()
; #define PG8_SCHED __builtin_amdgcn_sched_barrier(0)
; template <class Epi, class Sched>
; __device__ __forceinline__ void gemm_phase(LAS unsigned char* lds, const Gemm g, const Sched& S, const Epi& E, const int wv) {
;     ...
;             PG8_LDA(At, 1, 1); PG8_STAGE(PG8_SB(1, 0), b3, voffB); PG8_STAGE(PG8_SB(1, 1), b3 + hstep, voffB); PG8_STAGE(PG8_SA(1, 0), a3, voffA);
;             PG8_WAIT_V(8); PG8_WAIT_L(0); PG8_BAR; PG8_MMA(1, 0, At, B0); PG8_MMA(1, 1, At, B1); PG8_BAR; PG8_SCHED;
;         }
;         if (wr == 0) PG8_BAR;
	s_add_i32 s12, s43, s25
	v_lshl_add_u64 v[152:153], v[152:153], 0, s[46:47]
	s_mov_b32 m0, s12
	ds_read_b128 v[178:181], v157 offset:49152
	ds_read_b128 v[182:185], v157 offset:50176
	ds_read_b128 v[186:189], v157 offset:51200
	ds_read_b128 v[190:193], v157 offset:52224
	ds_read_b128 v[194:197], v157 offset:53248
	ds_read_b128 v[198:201], v157 offset:54272
	ds_read_b128 v[202:205], v157 offset:55296
	ds_read_b128 v[206:209], v157 offset:56320
	global_load_lds_dwordx4 v[152:153], off
	s_add_i32 m0, s12, 0x2000
	s_add_u32 s10, s10, 0x80080
	v_lshl_add_u64 v[152:153], v[212:213], 0, s[46:47]
	s_addc_u32 s11, s11, 0
	s_add_i32 s12, s44, s25
	global_load_lds_dwordx4 v[152:153], off
	v_lshl_add_u64 v[152:153], s[10:11], 0, v[132:133]
	s_mov_b32 m0, s12
	s_nop 0
	global_load_lds_dwordx4 v[152:153], off
	v_lshl_add_u64 v[152:153], s[10:11], 0, v[128:129]
	s_add_i32 m0, s12, 0x2000
	s_nop 0
	global_load_lds_dwordx4 v[152:153], off
	v_lshl_add_u64 v[152:153], v[214:215], 0, s[46:47]
	s_mov_b32 m0, s30
	s_nop 0
	global_load_lds_dwordx4 v[152:153], off
	v_lshl_add_u64 v[152:153], v[216:217], 0, s[46:47]
	s_mov_b32 m0, s31
	s_nop 0
	global_load_lds_dwordx4 v[152:153], off
	s_waitcnt vmcnt(8)
	s_waitcnt lgkmcnt(0)
	s_barrier
	s_setprio 1
	s_waitcnt lgkmcnt(0)
	v_mfma_f32_16x16x32_bf16 v[60:63], v[140:143], v[178:181], v[60:63]
	v_mfma_f32_16x16x32_bf16 v[52:55], v[148:151], v[178:181], v[52:55]
	v_mfma_f32_16x16x32_bf16 v[44:47], v[140:143], v[186:189], v[44:47]
	v_mfma_f32_16x16x32_bf16 v[36:39], v[148:151], v[186:189], v[36:39]
	v_mfma_f32_16x16x32_bf16 v[28:31], v[140:143], v[194:197], v[28:31]
	v_mfma_f32_16x16x32_bf16 v[20:23], v[148:151], v[194:197], v[20:23]
	v_mfma_f32_16x16x32_bf16 v[12:15], v[140:143], v[202:205], v[12:15]
	v_mfma_f32_16x16x32_bf16 v[4:7], v[148:151], v[202:205], v[4:7]
	v_mfma_f32_16x16x32_bf16 v[60:63], v[144:147], v[182:185], v[60:63]
	v_mfma_f32_16x16x32_bf16 v[52:55], v[158:161], v[182:185], v[52:55]
	v_mfma_f32_16x16x32_bf16 v[44:47], v[144:147], v[190:193], v[44:47]
	v_mfma_f32_16x16x32_bf16 v[36:39], v[158:161], v[190:193], v[36:39]
	v_mfma_f32_16x16x32_bf16 v[28:31], v[144:147], v[198:201], v[28:31]
	v_mfma_f32_16x16x32_bf16 v[20:23], v[158:161], v[198:201], v[20:23]
	v_mfma_f32_16x16x32_bf16 v[12:15], v[144:147], v[206:209], v[12:15]
	v_mfma_f32_16x16x32_bf16 v[4:7], v[158:161], v[206:209], v[4:7]
	v_mfma_f32_16x16x32_bf16 v[56:59], v[162:165], v[178:181], v[56:59]
	v_mfma_f32_16x16x32_bf16 v[48:51], v[170:173], v[178:181], v[48:51]
	v_mfma_f32_16x16x32_bf16 v[40:43], v[162:165], v[186:189], v[40:43]
	v_mfma_f32_16x16x32_bf16 v[32:35], v[170:173], v[186:189], v[32:35]
	v_mfma_f32_16x16x32_bf16 v[24:27], v[162:165], v[194:197], v[24:27]
	v_mfma_f32_16x16x32_bf16 v[16:19], v[170:173], v[194:197], v[16:19]
	v_mfma_f32_16x16x32_bf16 v[8:11], v[162:165], v[202:205], v[8:11]
	v_mfma_f32_16x16x32_bf16 v[0:3], v[170:173], v[202:205], v[0:3]
	v_mfma_f32_16x16x32_bf16 v[56:59], v[166:169], v[182:185], v[56:59]
	v_mfma_f32_16x16x32_bf16 v[48:51], v[174:177], v[182:185], v[48:51]
	v_mfma_f32_16x16x32_bf16 v[40:43], v[166:169], v[190:193], v[40:43]
	v_mfma_f32_16x16x32_bf16 v[32:35], v[174:177], v[190:193], v[32:35]
	v_mfma_f32_16x16x32_bf16 v[24:27], v[166:169], v[198:201], v[24:27]
	v_mfma_f32_16x16x32_bf16 v[16:19], v[174:177], v[198:201], v[16:19]
	v_mfma_f32_16x16x32_bf16 v[8:11], v[166:169], v[206:209], v[8:11]
	v_mfma_f32_16x16x32_bf16 v[0:3], v[174:177], v[206:209], v[0:3]
	s_setprio 0
	s_barrier
	s_add_i32 s42, s42, 2
	s_add_u32 s16, s16, 0x100
	s_addc_u32 s17, s17, 0
	s_add_u32 s40, s40, 0x100
	s_addc_u32 s41, s41, 0
	s_cmp_gt_u32 s42, 29
	s_cbranch_scc0 .LBB0_346
	s_and_b64 vcc, exec, s[8:9]
	s_cbranch_vccz .LBB0_349
	s_barrier
